# GLA k/q column loads (2-byte, once-read) marked non-temporal
# baseline (speedup 1.0000x reference)
.LBB0_468:
	v_mov_b32_e32 v38, v0
	v_readlane_b32 s0, v250, 43
	v_ashrrev_i32_e32 v129, 3, v38
	v_add_u32_e32 v6, s88, v129
	s_waitcnt lgkmcnt(0)
	v_ashrrev_i32_e32 v7, 31, v6
	v_lshlrev_b64 v[6:7], 7, v[6:7]
	v_readlane_b32 s1, v250, 44
	v_lshlrev_b32_e32 v1, 3, v38
	v_and_b32_e32 v138, 56, v1
	v_lshl_add_u64 v[6:7], s[0:1], 0, v[6:7]
	v_lshl_add_u64 v[6:7], v[6:7], 0, v[138:139]
	v_lshlrev_b32_sdwa v40, v230, v38 dst_sel:DWORD dst_unused:UNUSED_PAD src0_sel:DWORD src1_sel:BYTE_0
	v_mov_b32_e32 v41, v139
	v_readlane_b32 s0, v254, 41
	global_load_dwordx2 v[42:43], v[6:7], off
	v_lshl_add_u64 v[6:7], s[60:61], 0, v[40:41]
	v_readlane_b32 s1, v254, 42
	v_ashrrev_i32_e32 v121, 8, v38
	s_movk_i32 s4, 0x2800
	v_lshl_add_u64 v[8:9], v[6:7], 0, s[0:1]
	v_readlane_b32 s0, v254, 12
	v_readlane_b32 s1, v254, 13
	global_load_dword v99, v[8:9], off
	v_lshl_add_u32 v39, v121, 5, s88
	v_lshl_add_u64 v[8:9], v[6:7], 0, s[0:1]
	v_readlane_b32 s0, v254, 14
	v_readlane_b32 s1, v254, 15
	global_load_dword v100, v[8:9], off
	v_lshlrev_b32_sdwa v84, v227, v38 dst_sel:DWORD dst_unused:UNUSED_PAD src0_sel:DWORD src1_sel:BYTE_0
	v_lshl_add_u64 v[8:9], v[6:7], 0, s[0:1]
	v_readlane_b32 s0, v253, 56
	v_readlane_b32 s1, v253, 57
	global_load_dword v101, v[8:9], off
	v_mov_b32_e32 v85, v139
	v_lshl_add_u64 v[8:9], v[6:7], 0, s[0:1]
	v_readlane_b32 s0, v254, 16
	v_readlane_b32 s1, v254, 17
	global_load_dword v104, v[8:9], off
	v_or_b32_e32 v41, 1, v39
	v_lshl_add_u64 v[8:9], v[6:7], 0, s[0:1]
	v_readlane_b32 s0, v254, 18
	v_readlane_b32 s1, v254, 19
	global_load_dword v105, v[8:9], off
	v_ashrrev_i32_e32 v130, 6, v38
	v_lshl_add_u64 v[8:9], v[6:7], 0, s[0:1]
	v_readlane_b32 s0, v254, 20
	v_readlane_b32 s1, v254, 21
	global_load_dword v106, v[8:9], off
	v_add_u32_e32 v10, 0x200, v38
	v_lshl_add_u64 v[8:9], v[6:7], 0, s[0:1]
	v_readlane_b32 s0, v254, 22
	v_readlane_b32 s1, v254, 23
	global_load_dword v107, v[8:9], off
	v_mov_b32_e32 v45, v139
	v_lshl_add_u64 v[8:9], v[6:7], 0, s[0:1]
	v_readlane_b32 s0, v254, 45
	v_readlane_b32 s1, v254, 46
	global_load_dword v109, v[8:9], off
	v_ashrrev_i32_e32 v131, 6, v10
	v_lshl_add_u64 v[8:9], v[6:7], 0, s[0:1]
	v_readlane_b32 s0, v254, 24
	v_readlane_b32 s1, v254, 25
	global_load_dword v108, v[8:9], off
	v_add_u32_e32 v10, s88, v131
	v_lshl_add_u64 v[8:9], v[6:7], 0, s[0:1]
	v_readlane_b32 s0, v254, 26
	v_readlane_b32 s1, v254, 27
	global_load_dword v112, v[8:9], off
	v_add_u32_e32 v14, 0x400, v38
	v_lshl_add_u64 v[8:9], v[6:7], 0, s[0:1]
	v_readlane_b32 s0, v254, 28
	v_readlane_b32 s1, v254, 29
	global_load_dword v113, v[8:9], off
	v_ashrrev_i32_e32 v132, 6, v14
	v_lshl_add_u64 v[8:9], v[6:7], 0, s[0:1]
	v_readlane_b32 s0, v254, 30
	v_readlane_b32 s1, v254, 31
	global_load_dword v114, v[8:9], off
	v_add_u32_e32 v14, s88, v132
	v_lshl_add_u64 v[8:9], v[6:7], 0, s[0:1]
	v_readlane_b32 s0, v254, 32
	v_readlane_b32 s1, v254, 33
	global_load_dword v115, v[8:9], off
	v_add_u32_e32 v18, 0x600, v38
	v_lshl_add_u64 v[8:9], v[6:7], 0, s[0:1]
	v_readlane_b32 s0, v254, 34
	v_readlane_b32 s1, v254, 35
	global_load_dword v116, v[8:9], off
	v_ashrrev_i32_e32 v133, 6, v18
	v_lshl_add_u64 v[8:9], v[6:7], 0, s[0:1]
	v_readlane_b32 s0, v254, 36
	v_readlane_b32 s1, v254, 37
	global_load_dword v117, v[8:9], off
	v_add_u32_e32 v18, s88, v133
	v_lshl_add_u64 v[6:7], v[6:7], 0, s[0:1]
	v_readlane_b32 s0, v254, 38
	global_load_dword v120, v[6:7], off
	v_lshlrev_b32_e32 v8, 4, v38
	v_or_b32_sdwa v6, v38, s0 dst_sel:DWORD dst_unused:UNUSED_PAD src0_sel:BYTE_0 src1_sel:DWORD
	v_readlane_b32 s0, v251, 55
	v_readlane_b32 s1, v251, 56
	v_ashrrev_i32_e32 v7, 31, v6
	v_lshl_add_u64 v[6:7], v[6:7], 2, s[62:63]
	v_mov_b64_e32 v[46:47], s[0:1]
	v_mad_i64_i32 v[48:49], s[0:1], v39, s4, v[46:47]
	v_lshl_add_u64 v[86:87], v[48:49], 0, v[84:85]
	v_mad_i64_i32 v[48:49], s[0:1], v41, s4, v[46:47]
	v_or_b32_e32 v41, 2, v39
	v_lshl_add_u64 v[88:89], v[48:49], 0, v[84:85]
	v_mad_i64_i32 v[48:49], s[0:1], v41, s4, v[46:47]
	v_or_b32_e32 v41, 3, v39
	v_lshl_add_u64 v[90:91], v[48:49], 0, v[84:85]
	v_mad_i64_i32 v[48:49], s[0:1], v41, s4, v[46:47]
	v_or_b32_e32 v41, 4, v39
	v_lshl_add_u64 v[92:93], v[48:49], 0, v[84:85]
	v_mad_i64_i32 v[48:49], s[0:1], v41, s4, v[46:47]
	v_or_b32_e32 v41, 5, v39
	v_lshl_add_u64 v[94:95], v[48:49], 0, v[84:85]
	v_mad_i64_i32 v[48:49], s[0:1], v41, s4, v[46:47]
	v_or_b32_e32 v41, 6, v39
	v_lshl_add_u64 v[96:97], v[48:49], 0, v[84:85]
	v_mad_i64_i32 v[48:49], s[0:1], v41, s4, v[46:47]
	v_or_b32_e32 v41, 7, v39
	global_load_dword v122, v[6:7], off
	v_add_u32_e32 v6, s88, v130
	v_lshl_add_u64 v[140:141], v[48:49], 0, v[84:85]
	v_mad_i64_i32 v[48:49], s[0:1], v41, s4, v[46:47]
	v_or_b32_e32 v41, 8, v39
	v_mad_i64_i32 v[6:7], s[0:1], v6, s4, v[46:47]
	v_and_b32_e32 v44, 0x3f0, v8
	v_lshl_add_u64 v[142:143], v[48:49], 0, v[84:85]
	v_mad_i64_i32 v[48:49], s[0:1], v41, s4, v[46:47]
	v_or_b32_e32 v41, 9, v39
	v_lshl_add_u64 v[6:7], v[6:7], 0, v[44:45]
	v_lshl_add_u64 v[146:147], v[48:49], 0, v[84:85]
	v_mad_i64_i32 v[48:49], s[0:1], v41, s4, v[46:47]
	v_or_b32_e32 v41, 10, v39
	v_add_co_u32_e32 v6, vcc, s12, v6
	v_mad_i64_i32 v[10:11], s[0:1], v10, s4, v[46:47]
	v_lshl_add_u64 v[148:149], v[48:49], 0, v[84:85]
	v_mad_i64_i32 v[48:49], s[0:1], v41, s4, v[46:47]
	v_or_b32_e32 v41, 11, v39
	v_addc_co_u32_e32 v7, vcc, 0, v7, vcc
	v_lshl_add_u64 v[10:11], v[10:11], 0, v[44:45]
	v_lshl_add_u64 v[150:151], v[48:49], 0, v[84:85]
	v_mad_i64_i32 v[48:49], s[0:1], v41, s4, v[46:47]
	v_or_b32_e32 v41, 12, v39
	v_add_co_u32_e32 v10, vcc, s12, v10
	v_mad_i64_i32 v[14:15], s[0:1], v14, s4, v[46:47]
	v_lshl_add_u64 v[152:153], v[48:49], 0, v[84:85]
	v_mad_i64_i32 v[48:49], s[0:1], v41, s4, v[46:47]
	v_or_b32_e32 v41, 13, v39
	v_addc_co_u32_e32 v11, vcc, 0, v11, vcc
	v_lshl_add_u64 v[14:15], v[14:15], 0, v[44:45]
	v_add_u32_e32 v22, 0x800, v38
	v_lshl_add_u64 v[154:155], v[48:49], 0, v[84:85]
	v_mad_i64_i32 v[48:49], s[0:1], v41, s4, v[46:47]
	v_or_b32_e32 v41, 14, v39
	v_add_co_u32_e32 v14, vcc, s12, v14
	v_mad_i64_i32 v[18:19], s[0:1], v18, s4, v[46:47]
	v_ashrrev_i32_e32 v134, 6, v22
	v_lshl_add_u64 v[82:83], v[48:49], 0, v[84:85]
	v_mad_i64_i32 v[48:49], s[0:1], v41, s4, v[46:47]
	v_or_b32_e32 v41, 15, v39
	v_addc_co_u32_e32 v15, vcc, 0, v15, vcc
	v_lshl_add_u64 v[18:19], v[18:19], 0, v[44:45]
	v_add_u32_e32 v22, s88, v134
	v_add_u32_e32 v26, 0xa00, v38
	v_lshl_add_u64 v[80:81], v[48:49], 0, v[84:85]
	v_mad_i64_i32 v[48:49], s[0:1], v41, s4, v[46:47]
	v_or_b32_e32 v41, 16, v39
	v_add_co_u32_e32 v18, vcc, s12, v18
	v_mad_i64_i32 v[22:23], s[0:1], v22, s4, v[46:47]
	v_ashrrev_i32_e32 v135, 6, v26
	v_lshl_add_u64 v[78:79], v[48:49], 0, v[84:85]
	v_mad_i64_i32 v[48:49], s[0:1], v41, s4, v[46:47]
	v_or_b32_e32 v41, 17, v39
	v_addc_co_u32_e32 v19, vcc, 0, v19, vcc
	v_lshl_add_u64 v[22:23], v[22:23], 0, v[44:45]
	v_add_u32_e32 v26, s88, v135
	v_add_u32_e32 v30, 0xc00, v38
	v_lshl_add_u64 v[76:77], v[48:49], 0, v[84:85]
	v_mad_i64_i32 v[48:49], s[0:1], v41, s4, v[46:47]
	v_or_b32_e32 v41, 18, v39
	v_add_co_u32_e32 v22, vcc, s12, v22
	v_mad_i64_i32 v[26:27], s[0:1], v26, s4, v[46:47]
	v_ashrrev_i32_e32 v136, 6, v30
	v_lshl_add_u64 v[74:75], v[48:49], 0, v[84:85]
	v_mad_i64_i32 v[48:49], s[0:1], v41, s4, v[46:47]
	v_or_b32_e32 v41, 19, v39
	global_load_dwordx4 v[6:9], v[6:7], off offset:2048
	v_addc_co_u32_e32 v23, vcc, 0, v23, vcc
	v_lshl_add_u64 v[26:27], v[26:27], 0, v[44:45]
	v_add_u32_e32 v30, s88, v136
	v_add_u32_e32 v34, 0xe00, v38
	v_lshl_add_u64 v[72:73], v[48:49], 0, v[84:85]
	v_mad_i64_i32 v[48:49], s[0:1], v41, s4, v[46:47]
	v_or_b32_e32 v41, 20, v39
	global_load_dwordx4 v[10:13], v[10:11], off offset:2048
	v_add_co_u32_e32 v26, vcc, s12, v26
	v_mad_i64_i32 v[30:31], s[0:1], v30, s4, v[46:47]
	v_ashrrev_i32_e32 v137, 6, v34
	v_lshl_add_u64 v[70:71], v[48:49], 0, v[84:85]
	v_mad_i64_i32 v[48:49], s[0:1], v41, s4, v[46:47]
	v_or_b32_e32 v41, 21, v39
	global_load_dwordx4 v[14:17], v[14:15], off offset:2048
	v_addc_co_u32_e32 v27, vcc, 0, v27, vcc
	v_lshl_add_u64 v[30:31], v[30:31], 0, v[44:45]
	v_add_u32_e32 v34, s88, v137
	v_lshl_add_u64 v[68:69], v[48:49], 0, v[84:85]
	v_mad_i64_i32 v[48:49], s[0:1], v41, s4, v[46:47]
	v_or_b32_e32 v41, 22, v39
	global_load_dwordx4 v[18:21], v[18:19], off offset:2048
	v_add_co_u32_e32 v30, vcc, s12, v30
	v_mad_i64_i32 v[34:35], s[0:1], v34, s4, v[46:47]
	v_lshl_add_u64 v[66:67], v[48:49], 0, v[84:85]
	v_mad_i64_i32 v[48:49], s[0:1], v41, s4, v[46:47]
	v_or_b32_e32 v41, 23, v39
	global_load_dwordx4 v[22:25], v[22:23], off offset:2048
	v_addc_co_u32_e32 v31, vcc, 0, v31, vcc
	v_lshl_add_u64 v[34:35], v[34:35], 0, v[44:45]
	v_lshl_add_u64 v[64:65], v[48:49], 0, v[84:85]
	v_mad_i64_i32 v[48:49], s[0:1], v41, s4, v[46:47]
	v_or_b32_e32 v41, 24, v39
	global_load_dwordx4 v[26:29], v[26:27], off offset:2048
	v_add_co_u32_e32 v34, vcc, s12, v34
	v_lshl_add_u64 v[62:63], v[48:49], 0, v[84:85]
	v_mad_i64_i32 v[48:49], s[0:1], v41, s4, v[46:47]
	v_or_b32_e32 v41, 25, v39
	global_load_dwordx4 v[30:33], v[30:31], off offset:2048
	v_addc_co_u32_e32 v35, vcc, 0, v35, vcc
	v_lshl_add_u64 v[60:61], v[48:49], 0, v[84:85]
	v_mad_i64_i32 v[48:49], s[0:1], v41, s4, v[46:47]
	v_or_b32_e32 v41, 26, v39
	global_load_dwordx4 v[34:37], v[34:35], off offset:2048
	v_lshl_add_u64 v[58:59], v[48:49], 0, v[84:85]
	v_mad_i64_i32 v[48:49], s[0:1], v41, s4, v[46:47]
	v_or_b32_e32 v41, 27, v39
	v_lshl_add_u64 v[56:57], v[48:49], 0, v[84:85]
	v_mad_i64_i32 v[48:49], s[0:1], v41, s4, v[46:47]
	v_or_b32_e32 v41, 28, v39
	v_lshl_add_u64 v[54:55], v[48:49], 0, v[84:85]
	v_mad_i64_i32 v[48:49], s[0:1], v41, s4, v[46:47]
	v_or_b32_e32 v41, 29, v39
	v_lshl_add_u64 v[52:53], v[48:49], 0, v[84:85]
	v_mad_i64_i32 v[48:49], s[0:1], v41, s4, v[46:47]
	v_or_b32_e32 v41, 30, v39
	v_or_b32_e32 v39, 31, v39
	v_lshl_add_u64 v[50:51], v[48:49], 0, v[84:85]
	v_mad_i64_i32 v[48:49], s[0:1], v41, s4, v[46:47]
	v_mad_i64_i32 v[46:47], s[0:1], v39, s4, v[46:47]
	v_lshl_add_u64 v[48:49], v[48:49], 0, v[84:85]
	v_lshl_add_u64 v[46:47], v[46:47], 0, v[84:85]
	v_add_co_u32_e32 v84, vcc, s12, v86
	v_readlane_b32 s5, v253, 4
	s_nop 0
	v_addc_co_u32_e32 v85, vcc, 0, v87, vcc
	global_load_ushort v127, v[84:85], off offset:512 nt
	global_load_ushort v128, v[86:87], off offset:2048 nt
	v_add_co_u32_e32 v84, vcc, s12, v88
	v_readlane_b32 s0, v253, 5
	s_nop 0
	v_addc_co_u32_e32 v85, vcc, 0, v89, vcc
	global_load_ushort v125, v[84:85], off offset:512 nt
	global_load_ushort v126, v[88:89], off offset:2048 nt
	v_add_co_u32_e32 v84, vcc, s12, v90
	s_movk_i32 s4, 0x410
	s_nop 0
	v_addc_co_u32_e32 v85, vcc, 0, v91, vcc
	global_load_ushort v123, v[84:85], off offset:512 nt
	global_load_ushort v124, v[90:91], off offset:2048 nt
	v_add_co_u32_e32 v84, vcc, s12, v92
	v_readfirstlane_b32 s20, v38
	s_nop 0
	v_addc_co_u32_e32 v85, vcc, 0, v93, vcc
	global_load_ushort v118, v[84:85], off offset:512 nt
	global_load_ushort v119, v[92:93], off offset:2048 nt
	v_add_co_u32_e32 v84, vcc, s12, v94
	s_nop 1
	v_addc_co_u32_e32 v85, vcc, 0, v95, vcc
	global_load_ushort v110, v[84:85], off offset:512 nt
	global_load_ushort v111, v[94:95], off offset:2048 nt
	v_add_co_u32_e32 v84, vcc, s12, v96
	s_nop 1
	v_addc_co_u32_e32 v85, vcc, 0, v97, vcc
	global_load_ushort v102, v[84:85], off offset:512 nt
	global_load_ushort v103, v[96:97], off offset:2048 nt
	v_add_co_u32_e32 v84, vcc, s12, v140
	s_nop 1
	v_addc_co_u32_e32 v85, vcc, 0, v141, vcc
	global_load_ushort v97, v[84:85], off offset:512 nt
	global_load_ushort v98, v[140:141], off offset:2048 nt
	v_add_co_u32_e32 v84, vcc, s12, v142
	s_nop 1
	v_addc_co_u32_e32 v85, vcc, 0, v143, vcc
	global_load_ushort v95, v[84:85], off offset:512 nt
	global_load_ushort v96, v[142:143], off offset:2048 nt
	v_add_co_u32_e32 v84, vcc, s12, v146
	s_nop 1
	v_addc_co_u32_e32 v85, vcc, 0, v147, vcc
	global_load_ushort v93, v[84:85], off offset:512 nt
	global_load_ushort v94, v[146:147], off offset:2048 nt
	v_add_co_u32_e32 v84, vcc, s12, v148
	s_nop 1
	v_addc_co_u32_e32 v85, vcc, 0, v149, vcc
	global_load_ushort v91, v[84:85], off offset:512 nt
	global_load_ushort v92, v[148:149], off offset:2048 nt
	v_add_co_u32_e32 v84, vcc, s12, v150
	s_nop 1
	v_addc_co_u32_e32 v85, vcc, 0, v151, vcc
	global_load_ushort v89, v[84:85], off offset:512 nt
	global_load_ushort v90, v[150:151], off offset:2048 nt
	v_add_co_u32_e32 v84, vcc, s12, v152
	s_nop 1
	v_addc_co_u32_e32 v85, vcc, 0, v153, vcc
	global_load_ushort v87, v[84:85], off offset:512 nt
	global_load_ushort v88, v[152:153], off offset:2048 nt
	v_add_co_u32_e32 v84, vcc, s12, v154
	s_nop 1
	v_addc_co_u32_e32 v85, vcc, 0, v155, vcc
	v_add_co_u32_e32 v140, vcc, s12, v82
	global_load_ushort v85, v[84:85], off offset:512 nt
	s_nop 0
	global_load_ushort v86, v[154:155], off offset:2048 nt
	v_addc_co_u32_e32 v141, vcc, 0, v83, vcc
	global_load_ushort v84, v[140:141], off offset:512 nt
	s_nop 0
	global_load_ushort v83, v[82:83], off offset:2048 nt
	v_add_co_u32_e32 v140, vcc, s12, v80
	s_nop 1
	v_addc_co_u32_e32 v141, vcc, 0, v81, vcc
	global_load_ushort v82, v[140:141], off offset:512 nt
	s_nop 0
	global_load_ushort v81, v[80:81], off offset:2048 nt
	v_add_co_u32_e32 v140, vcc, s12, v78
	s_nop 1
	v_addc_co_u32_e32 v141, vcc, 0, v79, vcc
	global_load_ushort v80, v[140:141], off offset:512 nt
	s_nop 0
	global_load_ushort v79, v[78:79], off offset:2048 nt
	v_add_co_u32_e32 v140, vcc, s12, v76
	s_nop 1
	v_addc_co_u32_e32 v141, vcc, 0, v77, vcc
	global_load_ushort v78, v[140:141], off offset:512 nt
	s_nop 0
	global_load_ushort v77, v[76:77], off offset:2048 nt
	v_add_co_u32_e32 v140, vcc, s12, v74
	s_nop 1
	v_addc_co_u32_e32 v141, vcc, 0, v75, vcc
	global_load_ushort v76, v[140:141], off offset:512 nt
	s_nop 0
	global_load_ushort v75, v[74:75], off offset:2048 nt
	v_add_co_u32_e32 v140, vcc, s12, v72
	s_nop 1
	v_addc_co_u32_e32 v141, vcc, 0, v73, vcc
	global_load_ushort v74, v[140:141], off offset:512 nt
	s_nop 0
	global_load_ushort v73, v[72:73], off offset:2048 nt
	v_add_co_u32_e32 v140, vcc, s12, v70
	s_nop 1
	v_addc_co_u32_e32 v141, vcc, 0, v71, vcc
	global_load_ushort v72, v[140:141], off offset:512 nt
	s_nop 0
	global_load_ushort v71, v[70:71], off offset:2048 nt
	v_add_co_u32_e32 v140, vcc, s12, v68
	s_nop 1
	v_addc_co_u32_e32 v141, vcc, 0, v69, vcc
	global_load_ushort v70, v[140:141], off offset:512 nt
	s_nop 0
	global_load_ushort v69, v[68:69], off offset:2048 nt
	v_add_co_u32_e32 v140, vcc, s12, v66
	s_nop 1
	v_addc_co_u32_e32 v141, vcc, 0, v67, vcc
	global_load_ushort v68, v[140:141], off offset:512 nt
	s_nop 0
	global_load_ushort v67, v[66:67], off offset:2048 nt
	v_add_co_u32_e32 v140, vcc, s12, v64
	s_nop 1
	v_addc_co_u32_e32 v141, vcc, 0, v65, vcc
	global_load_ushort v66, v[140:141], off offset:512 nt
	s_nop 0
	global_load_ushort v65, v[64:65], off offset:2048 nt
	v_add_co_u32_e32 v140, vcc, s12, v62
	s_nop 1
	v_addc_co_u32_e32 v141, vcc, 0, v63, vcc
	global_load_ushort v64, v[140:141], off offset:512 nt
	s_nop 0
	global_load_ushort v63, v[62:63], off offset:2048 nt
	v_add_co_u32_e32 v140, vcc, s12, v60
	s_nop 1
	v_addc_co_u32_e32 v141, vcc, 0, v61, vcc
	global_load_ushort v62, v[140:141], off offset:512 nt
	s_nop 0
	global_load_ushort v61, v[60:61], off offset:2048 nt
	v_add_co_u32_e32 v140, vcc, s12, v58
	s_nop 1
	v_addc_co_u32_e32 v141, vcc, 0, v59, vcc
	global_load_ushort v60, v[140:141], off offset:512 nt
	s_nop 0
	global_load_ushort v59, v[58:59], off offset:2048 nt
	v_add_co_u32_e32 v140, vcc, s12, v56
	s_nop 1
	v_addc_co_u32_e32 v141, vcc, 0, v57, vcc
	global_load_ushort v58, v[140:141], off offset:512 nt
	s_nop 0
	global_load_ushort v57, v[56:57], off offset:2048 nt
	v_add_co_u32_e32 v140, vcc, s12, v54
	s_nop 1
	v_addc_co_u32_e32 v141, vcc, 0, v55, vcc
	global_load_ushort v56, v[140:141], off offset:512 nt
	s_nop 0
	global_load_ushort v55, v[54:55], off offset:2048 nt
	v_add_co_u32_e32 v140, vcc, s12, v52
	s_nop 1
	v_addc_co_u32_e32 v141, vcc, 0, v53, vcc
	global_load_ushort v54, v[140:141], off offset:512 nt
	s_nop 0
	global_load_ushort v53, v[52:53], off offset:2048 nt
	v_add_co_u32_e32 v140, vcc, s12, v50
	s_nop 1
	v_addc_co_u32_e32 v141, vcc, 0, v51, vcc
	global_load_ushort v52, v[140:141], off offset:512 nt
	s_nop 0
	global_load_ushort v50, v[50:51], off offset:2048 nt
	v_add_co_u32_e32 v140, vcc, s12, v48
	s_nop 1
	v_addc_co_u32_e32 v141, vcc, 0, v49, vcc
	global_load_ushort v45, v[140:141], off offset:512 nt
	s_nop 0
	global_load_ushort v48, v[48:49], off offset:2048 nt
	v_add_co_u32_e32 v140, vcc, s12, v46
	s_nop 1
	v_addc_co_u32_e32 v141, vcc, 0, v47, vcc
	global_load_ushort v39, v[140:141], off offset:512 nt
	global_load_ushort v41, v[46:47], off offset:2048 nt
	v_lshlrev_b32_e32 v46, 6, v129
	v_add3_u32 v46, s5, v46, v138
	s_waitcnt vmcnt(0)
	ds_write_b64 v46, v[42:43]
	v_add_u32_e32 v42, s0, v44
	v_mad_u64_u32 v[46:47], s[0:1], v130, s4, v[42:43]
	ds_write_b128 v46, v[6:9]
	v_mad_u64_u32 v[6:7], s[0:1], v131, s4, v[42:43]
	ds_write_b128 v6, v[10:13]
	v_mad_u64_u32 v[6:7], s[0:1], v132, s4, v[42:43]
	ds_write_b128 v6, v[14:17]
	v_mad_u64_u32 v[6:7], s[0:1], v133, s4, v[42:43]
	ds_write_b128 v6, v[18:21]
	v_mad_u64_u32 v[6:7], s[0:1], v134, s4, v[42:43]
	ds_write_b128 v6, v[22:25]
	v_mad_u64_u32 v[6:7], s[0:1], v135, s4, v[42:43]
	ds_write_b128 v6, v[26:29]
	v_mad_u64_u32 v[6:7], s[0:1], v136, s4, v[42:43]
	ds_write_b128 v6, v[30:33]
	v_mad_u64_u32 v[6:7], s[0:1], v137, s4, v[42:43]
	v_lshl_add_u32 v10, v121, 11, s5
	ds_write_b128 v6, v[34:37]
	s_waitcnt lgkmcnt(0)
	s_barrier
	v_readlane_b32 s0, v253, 6
	ds_read_b128 v[194:197], v10 offset:0
	ds_read_b128 v[198:201], v10 offset:16
	ds_read_b128 v[202:205], v10 offset:32
	ds_read_b128 v[206:209], v10 offset:48
	ds_read_b128 v[210:213], v10 offset:64
	ds_read_b128 v[214:217], v10 offset:80
	ds_read_b128 v[218:221], v10 offset:96
	ds_read_b128 v[236:239], v10 offset:112
	ds_read_b128 v[240:243], v10 offset:128
	ds_read_b128 v[244:247], v10 offset:144
	ds_read_b128 v[150:153], v10 offset:160
	ds_read_b128 v[156:159], v10 offset:176
	v_mov_b32_e32 v130, v99
	v_mov_b32_e32 v131, v100
	v_mov_b32_e32 v132, v101
	v_mov_b32_e32 v133, v104
	v_mov_b32_e32 v134, v105
	v_mov_b32_e32 v135, v106
	v_mov_b32_e32 v136, v107
	v_mov_b32_e32 v137, v109
	v_mov_b32_e32 v140, v108
	v_mov_b32_e32 v141, v112
	v_mov_b32_e32 v142, v113
	v_mov_b32_e32 v143, v114
	v_mov_b32_e32 v146, v115
	v_mov_b32_e32 v147, v116
	v_mov_b32_e32 v148, v117
	v_mov_b32_e32 v149, v120
	s_waitcnt lgkmcnt(4)
	v_pk_mul_f32 v[194:195], v[130:131], v[194:195]
	v_pk_mul_f32 v[210:211], v[130:131], v[210:211]
	v_pk_fma_f32 v[194:195], v[132:133], v[196:197], v[194:195]
	v_pk_fma_f32 v[210:211], v[132:133], v[212:213], v[210:211]
	v_pk_fma_f32 v[194:195], v[134:135], v[198:199], v[194:195]
	v_pk_fma_f32 v[210:211], v[134:135], v[214:215], v[210:211]
	v_pk_fma_f32 v[194:195], v[136:137], v[200:201], v[194:195]
	v_pk_fma_f32 v[210:211], v[136:137], v[216:217], v[210:211]
	v_pk_fma_f32 v[194:195], v[140:141], v[202:203], v[194:195]
	v_pk_fma_f32 v[210:211], v[140:141], v[218:219], v[210:211]
	v_pk_fma_f32 v[194:195], v[142:143], v[204:205], v[194:195]
	v_pk_fma_f32 v[210:211], v[142:143], v[220:221], v[210:211]
	v_pk_fma_f32 v[194:195], v[146:147], v[206:207], v[194:195]
	v_pk_fma_f32 v[210:211], v[146:147], v[236:237], v[210:211]
	v_pk_fma_f32 v[194:195], v[148:149], v[208:209], v[194:195]
	v_pk_fma_f32 v[210:211], v[148:149], v[238:239], v[210:211]
	v_add_f32_e32 v49, v194, v195
	v_add_f32_e32 v138, v210, v211
	v_add_f32_e32 v49, v122, v49
	v_add_f32_e32 v138, v122, v138
	v_max_f32_e64 v51, -v49, 0
	v_max_f32_e64 v161, -v138, 0
	v_mul_f32_e64 v129, |v49|, s13
	v_mul_f32_e64 v188, |v138|, s13
	v_exp_f32_e32 v129, v129
	v_exp_f32_e32 v188, v188
	v_add_f32_e32 v129, 1.0, v129
	v_add_f32_e32 v188, 1.0, v188
	v_log_f32_e32 v129, v129
	v_log_f32_e32 v188, v188
	v_fmac_f32_e32 v51, 0x3f317218, v129
	v_fmac_f32_e32 v161, 0x3f317218, v188
	ds_read_b128 v[194:197], v10 offset:192
	ds_read_b128 v[198:201], v10 offset:208
	ds_read_b128 v[202:205], v10 offset:224
	ds_read_b128 v[206:209], v10 offset:240
	ds_read_b128 v[210:213], v10 offset:256
	ds_read_b128 v[214:217], v10 offset:272
	ds_read_b128 v[218:221], v10 offset:288
	ds_read_b128 v[236:239], v10 offset:304
	v_mul_f32_e32 v6, 0xbd800000, v51
	v_fmamk_f32 v8, v161, 0xbd800000, v6
	s_waitcnt lgkmcnt(4)
	v_pk_mul_f32 v[240:241], v[130:131], v[240:241]
	v_pk_mul_f32 v[194:195], v[130:131], v[194:195]
	v_pk_fma_f32 v[240:241], v[132:133], v[242:243], v[240:241]
	v_pk_fma_f32 v[194:195], v[132:133], v[196:197], v[194:195]
	v_pk_fma_f32 v[240:241], v[134:135], v[244:245], v[240:241]
	v_pk_fma_f32 v[194:195], v[134:135], v[198:199], v[194:195]
	v_pk_fma_f32 v[240:241], v[136:137], v[246:247], v[240:241]
	v_pk_fma_f32 v[194:195], v[136:137], v[200:201], v[194:195]
	v_pk_fma_f32 v[240:241], v[140:141], v[150:151], v[240:241]
	v_pk_fma_f32 v[194:195], v[140:141], v[202:203], v[194:195]
	v_pk_fma_f32 v[240:241], v[142:143], v[152:153], v[240:241]
	v_pk_fma_f32 v[194:195], v[142:143], v[204:205], v[194:195]
	v_pk_fma_f32 v[240:241], v[146:147], v[156:157], v[240:241]
	v_pk_fma_f32 v[194:195], v[146:147], v[206:207], v[194:195]
	v_pk_fma_f32 v[240:241], v[148:149], v[158:159], v[240:241]
	v_pk_fma_f32 v[194:195], v[148:149], v[208:209], v[194:195]
	v_add_f32_e32 v49, v240, v241
	v_add_f32_e32 v138, v194, v195
	v_add_f32_e32 v49, v122, v49
	v_add_f32_e32 v138, v122, v138
	v_max_f32_e64 v51, -v49, 0
	v_max_f32_e64 v161, -v138, 0
	v_mul_f32_e64 v129, |v49|, s13
	v_mul_f32_e64 v188, |v138|, s13
	v_exp_f32_e32 v129, v129
	v_exp_f32_e32 v188, v188
	v_add_f32_e32 v129, 1.0, v129
	v_add_f32_e32 v188, 1.0, v188
	v_log_f32_e32 v129, v129
	v_log_f32_e32 v188, v188
	v_fmac_f32_e32 v51, 0x3f317218, v129
	v_fmac_f32_e32 v161, 0x3f317218, v188
	ds_read_b128 v[240:243], v10 offset:320
	ds_read_b128 v[244:247], v10 offset:336
	ds_read_b128 v[150:153], v10 offset:352
	ds_read_b128 v[156:159], v10 offset:368
	ds_read_b128 v[194:197], v10 offset:384
	ds_read_b128 v[198:201], v10 offset:400
	ds_read_b128 v[202:205], v10 offset:416
	ds_read_b128 v[206:209], v10 offset:432
	v_fmamk_f32 v7, v51, 0xbd800000, v8
	v_fmamk_f32 v11, v161, 0xbd800000, v7
	s_waitcnt lgkmcnt(4)
	v_pk_mul_f32 v[210:211], v[130:131], v[210:211]
	v_pk_mul_f32 v[240:241], v[130:131], v[240:241]
	v_pk_fma_f32 v[210:211], v[132:133], v[212:213], v[210:211]
	v_pk_fma_f32 v[240:241], v[132:133], v[242:243], v[240:241]
	v_pk_fma_f32 v[210:211], v[134:135], v[214:215], v[210:211]
	v_pk_fma_f32 v[240:241], v[134:135], v[244:245], v[240:241]
	v_pk_fma_f32 v[210:211], v[136:137], v[216:217], v[210:211]
	v_pk_fma_f32 v[240:241], v[136:137], v[246:247], v[240:241]
	v_pk_fma_f32 v[210:211], v[140:141], v[218:219], v[210:211]
	v_pk_fma_f32 v[240:241], v[140:141], v[150:151], v[240:241]
	v_pk_fma_f32 v[210:211], v[142:143], v[220:221], v[210:211]
	v_pk_fma_f32 v[240:241], v[142:143], v[152:153], v[240:241]
	v_pk_fma_f32 v[210:211], v[146:147], v[236:237], v[210:211]
	v_pk_fma_f32 v[240:241], v[146:147], v[156:157], v[240:241]
	v_pk_fma_f32 v[210:211], v[148:149], v[238:239], v[210:211]
	v_pk_fma_f32 v[240:241], v[148:149], v[158:159], v[240:241]
	v_add_f32_e32 v49, v210, v211
	v_add_f32_e32 v138, v240, v241
	v_add_f32_e32 v49, v122, v49
	v_add_f32_e32 v138, v122, v138
	v_max_f32_e64 v51, -v49, 0
	v_max_f32_e64 v161, -v138, 0
	v_mul_f32_e64 v129, |v49|, s13
	v_mul_f32_e64 v188, |v138|, s13
	v_exp_f32_e32 v129, v129
	v_exp_f32_e32 v188, v188
	v_add_f32_e32 v129, 1.0, v129
	v_add_f32_e32 v188, 1.0, v188
	v_log_f32_e32 v129, v129
	v_log_f32_e32 v188, v188
	v_fmac_f32_e32 v51, 0x3f317218, v129
	v_fmac_f32_e32 v161, 0x3f317218, v188
	ds_read_b128 v[210:213], v10 offset:448
	ds_read_b128 v[214:217], v10 offset:464
	ds_read_b128 v[218:221], v10 offset:480
	ds_read_b128 v[236:239], v10 offset:496
	ds_read_b128 v[240:243], v10 offset:512
	ds_read_b128 v[244:247], v10 offset:528
	ds_read_b128 v[150:153], v10 offset:544
	ds_read_b128 v[156:159], v10 offset:560
	v_fmamk_f32 v9, v51, 0xbd800000, v11
	v_fmamk_f32 v13, v161, 0xbd800000, v9
	s_waitcnt lgkmcnt(4)
	v_pk_mul_f32 v[194:195], v[130:131], v[194:195]
	v_pk_mul_f32 v[210:211], v[130:131], v[210:211]
	v_pk_fma_f32 v[194:195], v[132:133], v[196:197], v[194:195]
	v_pk_fma_f32 v[210:211], v[132:133], v[212:213], v[210:211]
	v_pk_fma_f32 v[194:195], v[134:135], v[198:199], v[194:195]
	v_pk_fma_f32 v[210:211], v[134:135], v[214:215], v[210:211]
	v_pk_fma_f32 v[194:195], v[136:137], v[200:201], v[194:195]
	v_pk_fma_f32 v[210:211], v[136:137], v[216:217], v[210:211]
	v_pk_fma_f32 v[194:195], v[140:141], v[202:203], v[194:195]
	v_pk_fma_f32 v[210:211], v[140:141], v[218:219], v[210:211]
	v_pk_fma_f32 v[194:195], v[142:143], v[204:205], v[194:195]
	v_pk_fma_f32 v[210:211], v[142:143], v[220:221], v[210:211]
	v_pk_fma_f32 v[194:195], v[146:147], v[206:207], v[194:195]
	v_pk_fma_f32 v[210:211], v[146:147], v[236:237], v[210:211]
	v_pk_fma_f32 v[194:195], v[148:149], v[208:209], v[194:195]
	v_pk_fma_f32 v[210:211], v[148:149], v[238:239], v[210:211]
	v_add_f32_e32 v49, v194, v195
	v_add_f32_e32 v138, v210, v211
	v_add_f32_e32 v49, v122, v49
	v_add_f32_e32 v138, v122, v138
	v_max_f32_e64 v51, -v49, 0
	v_max_f32_e64 v161, -v138, 0
	v_mul_f32_e64 v129, |v49|, s13
	v_mul_f32_e64 v188, |v138|, s13
	v_exp_f32_e32 v129, v129
	v_exp_f32_e32 v188, v188
	v_add_f32_e32 v129, 1.0, v129
	v_add_f32_e32 v188, 1.0, v188
	v_log_f32_e32 v129, v129
	v_log_f32_e32 v188, v188
	v_fmac_f32_e32 v51, 0x3f317218, v129
	v_fmac_f32_e32 v161, 0x3f317218, v188
	ds_read_b128 v[194:197], v10 offset:576
	ds_read_b128 v[198:201], v10 offset:592
	ds_read_b128 v[202:205], v10 offset:608
	ds_read_b128 v[206:209], v10 offset:624
	ds_read_b128 v[210:213], v10 offset:640
	ds_read_b128 v[214:217], v10 offset:656
	ds_read_b128 v[218:221], v10 offset:672
	ds_read_b128 v[236:239], v10 offset:688
	v_fmamk_f32 v12, v51, 0xbd800000, v13
	v_fmamk_f32 v15, v161, 0xbd800000, v12
	s_waitcnt lgkmcnt(4)
	v_pk_mul_f32 v[240:241], v[130:131], v[240:241]
	v_pk_mul_f32 v[194:195], v[130:131], v[194:195]
	v_pk_fma_f32 v[240:241], v[132:133], v[242:243], v[240:241]
	v_pk_fma_f32 v[194:195], v[132:133], v[196:197], v[194:195]
	v_pk_fma_f32 v[240:241], v[134:135], v[244:245], v[240:241]
	v_pk_fma_f32 v[194:195], v[134:135], v[198:199], v[194:195]
	v_pk_fma_f32 v[240:241], v[136:137], v[246:247], v[240:241]
	v_pk_fma_f32 v[194:195], v[136:137], v[200:201], v[194:195]
	v_pk_fma_f32 v[240:241], v[140:141], v[150:151], v[240:241]
	v_pk_fma_f32 v[194:195], v[140:141], v[202:203], v[194:195]
	v_pk_fma_f32 v[240:241], v[142:143], v[152:153], v[240:241]
	v_pk_fma_f32 v[194:195], v[142:143], v[204:205], v[194:195]
	v_pk_fma_f32 v[240:241], v[146:147], v[156:157], v[240:241]
	v_pk_fma_f32 v[194:195], v[146:147], v[206:207], v[194:195]
	v_pk_fma_f32 v[240:241], v[148:149], v[158:159], v[240:241]
	v_pk_fma_f32 v[194:195], v[148:149], v[208:209], v[194:195]
	v_add_f32_e32 v49, v240, v241
	v_add_f32_e32 v138, v194, v195
	v_add_f32_e32 v49, v122, v49
	v_add_f32_e32 v138, v122, v138
	v_max_f32_e64 v51, -v49, 0
	v_max_f32_e64 v161, -v138, 0
	v_mul_f32_e64 v129, |v49|, s13
	v_mul_f32_e64 v188, |v138|, s13
	v_exp_f32_e32 v129, v129
	v_exp_f32_e32 v188, v188
	v_add_f32_e32 v129, 1.0, v129
	v_add_f32_e32 v188, 1.0, v188
	v_log_f32_e32 v129, v129
	v_log_f32_e32 v188, v188
	v_fmac_f32_e32 v51, 0x3f317218, v129
	v_fmac_f32_e32 v161, 0x3f317218, v188
	ds_read_b128 v[240:243], v10 offset:704
	ds_read_b128 v[244:247], v10 offset:720
	ds_read_b128 v[150:153], v10 offset:736
	ds_read_b128 v[156:159], v10 offset:752
	ds_read_b128 v[194:197], v10 offset:768
	ds_read_b128 v[198:201], v10 offset:784
	ds_read_b128 v[202:205], v10 offset:800
	ds_read_b128 v[206:209], v10 offset:816
	v_fmamk_f32 v14, v51, 0xbd800000, v15
	v_fmamk_f32 v17, v161, 0xbd800000, v14
	s_waitcnt lgkmcnt(4)
	v_pk_mul_f32 v[210:211], v[130:131], v[210:211]
	v_pk_mul_f32 v[240:241], v[130:131], v[240:241]
	v_pk_fma_f32 v[210:211], v[132:133], v[212:213], v[210:211]
	v_pk_fma_f32 v[240:241], v[132:133], v[242:243], v[240:241]
	v_pk_fma_f32 v[210:211], v[134:135], v[214:215], v[210:211]
	v_pk_fma_f32 v[240:241], v[134:135], v[244:245], v[240:241]
	v_pk_fma_f32 v[210:211], v[136:137], v[216:217], v[210:211]
	v_pk_fma_f32 v[240:241], v[136:137], v[246:247], v[240:241]
	v_pk_fma_f32 v[210:211], v[140:141], v[218:219], v[210:211]
	v_pk_fma_f32 v[240:241], v[140:141], v[150:151], v[240:241]
	v_pk_fma_f32 v[210:211], v[142:143], v[220:221], v[210:211]
	v_pk_fma_f32 v[240:241], v[142:143], v[152:153], v[240:241]
	v_pk_fma_f32 v[210:211], v[146:147], v[236:237], v[210:211]
	v_pk_fma_f32 v[240:241], v[146:147], v[156:157], v[240:241]
	v_pk_fma_f32 v[210:211], v[148:149], v[238:239], v[210:211]
	v_pk_fma_f32 v[240:241], v[148:149], v[158:159], v[240:241]
	v_add_f32_e32 v49, v210, v211
	v_add_f32_e32 v138, v240, v241
	v_add_f32_e32 v49, v122, v49
	v_add_f32_e32 v138, v122, v138
	v_max_f32_e64 v51, -v49, 0
	v_max_f32_e64 v161, -v138, 0
	v_mul_f32_e64 v129, |v49|, s13
	v_mul_f32_e64 v188, |v138|, s13
	v_exp_f32_e32 v129, v129
	v_exp_f32_e32 v188, v188
	v_add_f32_e32 v129, 1.0, v129
	v_add_f32_e32 v188, 1.0, v188
	v_log_f32_e32 v129, v129
	v_log_f32_e32 v188, v188
	v_fmac_f32_e32 v51, 0x3f317218, v129
	v_fmac_f32_e32 v161, 0x3f317218, v188
	ds_read_b128 v[210:213], v10 offset:832
	ds_read_b128 v[214:217], v10 offset:848
	ds_read_b128 v[218:221], v10 offset:864
	ds_read_b128 v[236:239], v10 offset:880
	ds_read_b128 v[240:243], v10 offset:896
	ds_read_b128 v[244:247], v10 offset:912
	ds_read_b128 v[150:153], v10 offset:928
	ds_read_b128 v[156:159], v10 offset:944
	v_fmamk_f32 v16, v51, 0xbd800000, v17
	v_fmamk_f32 v19, v161, 0xbd800000, v16
	s_waitcnt lgkmcnt(4)
	v_pk_mul_f32 v[194:195], v[130:131], v[194:195]
	v_pk_mul_f32 v[210:211], v[130:131], v[210:211]
	v_pk_fma_f32 v[194:195], v[132:133], v[196:197], v[194:195]
	v_pk_fma_f32 v[210:211], v[132:133], v[212:213], v[210:211]
	v_pk_fma_f32 v[194:195], v[134:135], v[198:199], v[194:195]
	v_pk_fma_f32 v[210:211], v[134:135], v[214:215], v[210:211]
	v_pk_fma_f32 v[194:195], v[136:137], v[200:201], v[194:195]
	v_pk_fma_f32 v[210:211], v[136:137], v[216:217], v[210:211]
	v_pk_fma_f32 v[194:195], v[140:141], v[202:203], v[194:195]
	v_pk_fma_f32 v[210:211], v[140:141], v[218:219], v[210:211]
	v_pk_fma_f32 v[194:195], v[142:143], v[204:205], v[194:195]
	v_pk_fma_f32 v[210:211], v[142:143], v[220:221], v[210:211]
	v_pk_fma_f32 v[194:195], v[146:147], v[206:207], v[194:195]
	v_pk_fma_f32 v[210:211], v[146:147], v[236:237], v[210:211]
	v_pk_fma_f32 v[194:195], v[148:149], v[208:209], v[194:195]
	v_pk_fma_f32 v[210:211], v[148:149], v[238:239], v[210:211]
	v_add_f32_e32 v49, v194, v195
	v_add_f32_e32 v138, v210, v211
	v_add_f32_e32 v49, v122, v49
	v_add_f32_e32 v138, v122, v138
	v_max_f32_e64 v51, -v49, 0
	v_max_f32_e64 v161, -v138, 0
	v_mul_f32_e64 v129, |v49|, s13
	v_mul_f32_e64 v188, |v138|, s13
	v_exp_f32_e32 v129, v129
	v_exp_f32_e32 v188, v188
	v_add_f32_e32 v129, 1.0, v129
	v_add_f32_e32 v188, 1.0, v188
	v_log_f32_e32 v129, v129
	v_log_f32_e32 v188, v188
	v_fmac_f32_e32 v51, 0x3f317218, v129
	v_fmac_f32_e32 v161, 0x3f317218, v188
	ds_read_b128 v[194:197], v10 offset:960
	ds_read_b128 v[198:201], v10 offset:976
	ds_read_b128 v[202:205], v10 offset:992
	ds_read_b128 v[206:209], v10 offset:1008
	ds_read_b128 v[210:213], v10 offset:1024
	ds_read_b128 v[214:217], v10 offset:1040
	ds_read_b128 v[218:221], v10 offset:1056
	ds_read_b128 v[236:239], v10 offset:1072
	v_fmamk_f32 v18, v51, 0xbd800000, v19
	v_fmamk_f32 v21, v161, 0xbd800000, v18
	s_waitcnt lgkmcnt(4)
	v_pk_mul_f32 v[240:241], v[130:131], v[240:241]
	v_pk_mul_f32 v[194:195], v[130:131], v[194:195]
	v_pk_fma_f32 v[240:241], v[132:133], v[242:243], v[240:241]
	v_pk_fma_f32 v[194:195], v[132:133], v[196:197], v[194:195]
	v_pk_fma_f32 v[240:241], v[134:135], v[244:245], v[240:241]
	v_pk_fma_f32 v[194:195], v[134:135], v[198:199], v[194:195]
	v_pk_fma_f32 v[240:241], v[136:137], v[246:247], v[240:241]
	v_pk_fma_f32 v[194:195], v[136:137], v[200:201], v[194:195]
	v_pk_fma_f32 v[240:241], v[140:141], v[150:151], v[240:241]
	v_pk_fma_f32 v[194:195], v[140:141], v[202:203], v[194:195]
	v_pk_fma_f32 v[240:241], v[142:143], v[152:153], v[240:241]
	v_pk_fma_f32 v[194:195], v[142:143], v[204:205], v[194:195]
	v_pk_fma_f32 v[240:241], v[146:147], v[156:157], v[240:241]
	v_pk_fma_f32 v[194:195], v[146:147], v[206:207], v[194:195]
	v_pk_fma_f32 v[240:241], v[148:149], v[158:159], v[240:241]
	v_pk_fma_f32 v[194:195], v[148:149], v[208:209], v[194:195]
	v_add_f32_e32 v49, v240, v241
	v_add_f32_e32 v138, v194, v195
	v_add_f32_e32 v49, v122, v49
	v_add_f32_e32 v138, v122, v138
	v_max_f32_e64 v51, -v49, 0
	v_max_f32_e64 v161, -v138, 0
	v_mul_f32_e64 v129, |v49|, s13
	v_mul_f32_e64 v188, |v138|, s13
	v_exp_f32_e32 v129, v129
	v_exp_f32_e32 v188, v188
	v_add_f32_e32 v129, 1.0, v129
	v_add_f32_e32 v188, 1.0, v188
	v_log_f32_e32 v129, v129
	v_log_f32_e32 v188, v188
	v_fmac_f32_e32 v51, 0x3f317218, v129
	v_fmac_f32_e32 v161, 0x3f317218, v188
	ds_read_b128 v[240:243], v10 offset:1088
	ds_read_b128 v[244:247], v10 offset:1104
	ds_read_b128 v[150:153], v10 offset:1120
	ds_read_b128 v[156:159], v10 offset:1136
	ds_read_b128 v[194:197], v10 offset:1152
	ds_read_b128 v[198:201], v10 offset:1168
	ds_read_b128 v[202:205], v10 offset:1184
	ds_read_b128 v[206:209], v10 offset:1200
	v_fmamk_f32 v20, v51, 0xbd800000, v21
	v_fmamk_f32 v23, v161, 0xbd800000, v20
	s_waitcnt lgkmcnt(4)
	v_pk_mul_f32 v[210:211], v[130:131], v[210:211]
	v_pk_mul_f32 v[240:241], v[130:131], v[240:241]
	v_pk_fma_f32 v[210:211], v[132:133], v[212:213], v[210:211]
	v_pk_fma_f32 v[240:241], v[132:133], v[242:243], v[240:241]
	v_pk_fma_f32 v[210:211], v[134:135], v[214:215], v[210:211]
	v_pk_fma_f32 v[240:241], v[134:135], v[244:245], v[240:241]
	v_pk_fma_f32 v[210:211], v[136:137], v[216:217], v[210:211]
	v_pk_fma_f32 v[240:241], v[136:137], v[246:247], v[240:241]
	v_pk_fma_f32 v[210:211], v[140:141], v[218:219], v[210:211]
	v_pk_fma_f32 v[240:241], v[140:141], v[150:151], v[240:241]
	v_pk_fma_f32 v[210:211], v[142:143], v[220:221], v[210:211]
	v_pk_fma_f32 v[240:241], v[142:143], v[152:153], v[240:241]
	v_pk_fma_f32 v[210:211], v[146:147], v[236:237], v[210:211]
	v_pk_fma_f32 v[240:241], v[146:147], v[156:157], v[240:241]
	v_pk_fma_f32 v[210:211], v[148:149], v[238:239], v[210:211]
	v_pk_fma_f32 v[240:241], v[148:149], v[158:159], v[240:241]
	v_add_f32_e32 v49, v210, v211
	v_add_f32_e32 v138, v240, v241
	v_add_f32_e32 v49, v122, v49
	v_add_f32_e32 v138, v122, v138
	v_max_f32_e64 v51, -v49, 0
	v_max_f32_e64 v161, -v138, 0
	v_mul_f32_e64 v129, |v49|, s13
	v_mul_f32_e64 v188, |v138|, s13
	v_exp_f32_e32 v129, v129
	v_exp_f32_e32 v188, v188
	v_add_f32_e32 v129, 1.0, v129
	v_add_f32_e32 v188, 1.0, v188
	v_log_f32_e32 v129, v129
	v_log_f32_e32 v188, v188
	v_fmac_f32_e32 v51, 0x3f317218, v129
	v_fmac_f32_e32 v161, 0x3f317218, v188
	ds_read_b128 v[210:213], v10 offset:1216
	ds_read_b128 v[214:217], v10 offset:1232
	ds_read_b128 v[218:221], v10 offset:1248
	ds_read_b128 v[236:239], v10 offset:1264
	ds_read_b128 v[240:243], v10 offset:1280
	ds_read_b128 v[244:247], v10 offset:1296
	ds_read_b128 v[150:153], v10 offset:1312
	ds_read_b128 v[156:159], v10 offset:1328
	v_fmamk_f32 v22, v51, 0xbd800000, v23
	v_fmamk_f32 v25, v161, 0xbd800000, v22
	s_waitcnt lgkmcnt(4)
	v_pk_mul_f32 v[194:195], v[130:131], v[194:195]
	v_pk_mul_f32 v[210:211], v[130:131], v[210:211]
	v_pk_fma_f32 v[194:195], v[132:133], v[196:197], v[194:195]
	v_pk_fma_f32 v[210:211], v[132:133], v[212:213], v[210:211]
	v_pk_fma_f32 v[194:195], v[134:135], v[198:199], v[194:195]
	v_pk_fma_f32 v[210:211], v[134:135], v[214:215], v[210:211]
	v_pk_fma_f32 v[194:195], v[136:137], v[200:201], v[194:195]
	v_pk_fma_f32 v[210:211], v[136:137], v[216:217], v[210:211]
	v_pk_fma_f32 v[194:195], v[140:141], v[202:203], v[194:195]
	v_pk_fma_f32 v[210:211], v[140:141], v[218:219], v[210:211]
	v_pk_fma_f32 v[194:195], v[142:143], v[204:205], v[194:195]
	v_pk_fma_f32 v[210:211], v[142:143], v[220:221], v[210:211]
	v_pk_fma_f32 v[194:195], v[146:147], v[206:207], v[194:195]
	v_pk_fma_f32 v[210:211], v[146:147], v[236:237], v[210:211]
	v_pk_fma_f32 v[194:195], v[148:149], v[208:209], v[194:195]
	v_pk_fma_f32 v[210:211], v[148:149], v[238:239], v[210:211]
	v_add_f32_e32 v49, v194, v195
	v_add_f32_e32 v138, v210, v211
	v_add_f32_e32 v49, v122, v49
	v_add_f32_e32 v138, v122, v138
	v_max_f32_e64 v51, -v49, 0
	v_max_f32_e64 v161, -v138, 0
	v_mul_f32_e64 v129, |v49|, s13
	v_mul_f32_e64 v188, |v138|, s13
	v_exp_f32_e32 v129, v129
	v_exp_f32_e32 v188, v188
	v_add_f32_e32 v129, 1.0, v129
	v_add_f32_e32 v188, 1.0, v188
	v_log_f32_e32 v129, v129
	v_log_f32_e32 v188, v188
	v_fmac_f32_e32 v51, 0x3f317218, v129
	v_fmac_f32_e32 v161, 0x3f317218, v188
	ds_read_b128 v[194:197], v10 offset:1344
	ds_read_b128 v[198:201], v10 offset:1360
	ds_read_b128 v[202:205], v10 offset:1376
	ds_read_b128 v[206:209], v10 offset:1392
	ds_read_b128 v[210:213], v10 offset:1408
	ds_read_b128 v[214:217], v10 offset:1424
	ds_read_b128 v[218:221], v10 offset:1440
	ds_read_b128 v[236:239], v10 offset:1456
	v_fmamk_f32 v24, v51, 0xbd800000, v25
	v_fmamk_f32 v27, v161, 0xbd800000, v24
	s_waitcnt lgkmcnt(4)
	v_pk_mul_f32 v[240:241], v[130:131], v[240:241]
	v_pk_mul_f32 v[194:195], v[130:131], v[194:195]
	v_pk_fma_f32 v[240:241], v[132:133], v[242:243], v[240:241]
	v_pk_fma_f32 v[194:195], v[132:133], v[196:197], v[194:195]
	v_pk_fma_f32 v[240:241], v[134:135], v[244:245], v[240:241]
	v_pk_fma_f32 v[194:195], v[134:135], v[198:199], v[194:195]
	v_pk_fma_f32 v[240:241], v[136:137], v[246:247], v[240:241]
	v_pk_fma_f32 v[194:195], v[136:137], v[200:201], v[194:195]
	v_pk_fma_f32 v[240:241], v[140:141], v[150:151], v[240:241]
	v_pk_fma_f32 v[194:195], v[140:141], v[202:203], v[194:195]
	v_pk_fma_f32 v[240:241], v[142:143], v[152:153], v[240:241]
	v_pk_fma_f32 v[194:195], v[142:143], v[204:205], v[194:195]
	v_pk_fma_f32 v[240:241], v[146:147], v[156:157], v[240:241]
	v_pk_fma_f32 v[194:195], v[146:147], v[206:207], v[194:195]
	v_pk_fma_f32 v[240:241], v[148:149], v[158:159], v[240:241]
	v_pk_fma_f32 v[194:195], v[148:149], v[208:209], v[194:195]
	v_add_f32_e32 v49, v240, v241
	v_add_f32_e32 v138, v194, v195
	v_add_f32_e32 v49, v122, v49
	v_add_f32_e32 v138, v122, v138
	v_max_f32_e64 v51, -v49, 0
	v_max_f32_e64 v161, -v138, 0
	v_mul_f32_e64 v129, |v49|, s13
	v_mul_f32_e64 v188, |v138|, s13
	v_exp_f32_e32 v129, v129
	v_exp_f32_e32 v188, v188
	v_add_f32_e32 v129, 1.0, v129
	v_add_f32_e32 v188, 1.0, v188
	v_log_f32_e32 v129, v129
	v_log_f32_e32 v188, v188
	v_fmac_f32_e32 v51, 0x3f317218, v129
	v_fmac_f32_e32 v161, 0x3f317218, v188
	ds_read_b128 v[240:243], v10 offset:1472
	ds_read_b128 v[244:247], v10 offset:1488
	ds_read_b128 v[150:153], v10 offset:1504
	ds_read_b128 v[156:159], v10 offset:1520
	ds_read_b128 v[194:197], v10 offset:1536
	ds_read_b128 v[198:201], v10 offset:1552
	ds_read_b128 v[202:205], v10 offset:1568
	ds_read_b128 v[206:209], v10 offset:1584
	v_fmamk_f32 v26, v51, 0xbd800000, v27
	v_fmamk_f32 v29, v161, 0xbd800000, v26
	s_waitcnt lgkmcnt(4)
	v_pk_mul_f32 v[210:211], v[130:131], v[210:211]
	v_pk_mul_f32 v[240:241], v[130:131], v[240:241]
	v_pk_fma_f32 v[210:211], v[132:133], v[212:213], v[210:211]
	v_pk_fma_f32 v[240:241], v[132:133], v[242:243], v[240:241]
	v_pk_fma_f32 v[210:211], v[134:135], v[214:215], v[210:211]
	v_pk_fma_f32 v[240:241], v[134:135], v[244:245], v[240:241]
	v_pk_fma_f32 v[210:211], v[136:137], v[216:217], v[210:211]
	v_pk_fma_f32 v[240:241], v[136:137], v[246:247], v[240:241]
	v_pk_fma_f32 v[210:211], v[140:141], v[218:219], v[210:211]
	v_pk_fma_f32 v[240:241], v[140:141], v[150:151], v[240:241]
	v_pk_fma_f32 v[210:211], v[142:143], v[220:221], v[210:211]
	v_pk_fma_f32 v[240:241], v[142:143], v[152:153], v[240:241]
	v_pk_fma_f32 v[210:211], v[146:147], v[236:237], v[210:211]
	v_pk_fma_f32 v[240:241], v[146:147], v[156:157], v[240:241]
	v_pk_fma_f32 v[210:211], v[148:149], v[238:239], v[210:211]
	v_pk_fma_f32 v[240:241], v[148:149], v[158:159], v[240:241]
	v_add_f32_e32 v49, v210, v211
	v_add_f32_e32 v138, v240, v241
	v_add_f32_e32 v49, v122, v49
	v_add_f32_e32 v138, v122, v138
	v_max_f32_e64 v51, -v49, 0
	v_max_f32_e64 v161, -v138, 0
	v_mul_f32_e64 v129, |v49|, s13
	v_mul_f32_e64 v188, |v138|, s13
	v_exp_f32_e32 v129, v129
	v_exp_f32_e32 v188, v188
	v_add_f32_e32 v129, 1.0, v129
	v_add_f32_e32 v188, 1.0, v188
	v_log_f32_e32 v129, v129
	v_log_f32_e32 v188, v188
	v_fmac_f32_e32 v51, 0x3f317218, v129
	v_fmac_f32_e32 v161, 0x3f317218, v188
	ds_read_b128 v[210:213], v10 offset:1600
	ds_read_b128 v[214:217], v10 offset:1616
	ds_read_b128 v[218:221], v10 offset:1632
	ds_read_b128 v[236:239], v10 offset:1648
	ds_read_b128 v[240:243], v10 offset:1664
	ds_read_b128 v[244:247], v10 offset:1680
	ds_read_b128 v[150:153], v10 offset:1696
	ds_read_b128 v[156:159], v10 offset:1712
	v_fmamk_f32 v28, v51, 0xbd800000, v29
	v_fmamk_f32 v31, v161, 0xbd800000, v28
	s_waitcnt lgkmcnt(4)
	v_pk_mul_f32 v[194:195], v[130:131], v[194:195]
	v_pk_mul_f32 v[210:211], v[130:131], v[210:211]
	v_pk_fma_f32 v[194:195], v[132:133], v[196:197], v[194:195]
	v_pk_fma_f32 v[210:211], v[132:133], v[212:213], v[210:211]
	v_pk_fma_f32 v[194:195], v[134:135], v[198:199], v[194:195]
	v_pk_fma_f32 v[210:211], v[134:135], v[214:215], v[210:211]
	v_pk_fma_f32 v[194:195], v[136:137], v[200:201], v[194:195]
	v_pk_fma_f32 v[210:211], v[136:137], v[216:217], v[210:211]
	v_pk_fma_f32 v[194:195], v[140:141], v[202:203], v[194:195]
	v_pk_fma_f32 v[210:211], v[140:141], v[218:219], v[210:211]
	v_pk_fma_f32 v[194:195], v[142:143], v[204:205], v[194:195]
	v_pk_fma_f32 v[210:211], v[142:143], v[220:221], v[210:211]
	v_pk_fma_f32 v[194:195], v[146:147], v[206:207], v[194:195]
	v_pk_fma_f32 v[210:211], v[146:147], v[236:237], v[210:211]
	v_pk_fma_f32 v[194:195], v[148:149], v[208:209], v[194:195]
	v_pk_fma_f32 v[210:211], v[148:149], v[238:239], v[210:211]
	v_add_f32_e32 v49, v194, v195
	v_add_f32_e32 v138, v210, v211
	v_add_f32_e32 v49, v122, v49
	v_add_f32_e32 v138, v122, v138
	v_max_f32_e64 v51, -v49, 0
	v_max_f32_e64 v161, -v138, 0
	v_mul_f32_e64 v129, |v49|, s13
	v_mul_f32_e64 v188, |v138|, s13
	v_exp_f32_e32 v129, v129
	v_exp_f32_e32 v188, v188
	v_add_f32_e32 v129, 1.0, v129
	v_add_f32_e32 v188, 1.0, v188
	v_log_f32_e32 v129, v129
	v_log_f32_e32 v188, v188
	v_fmac_f32_e32 v51, 0x3f317218, v129
	v_fmac_f32_e32 v161, 0x3f317218, v188
	ds_read_b128 v[194:197], v10 offset:1728
	ds_read_b128 v[198:201], v10 offset:1744
	ds_read_b128 v[202:205], v10 offset:1760
	ds_read_b128 v[206:209], v10 offset:1776
	ds_read_b128 v[210:213], v10 offset:1792
	ds_read_b128 v[214:217], v10 offset:1808
	ds_read_b128 v[218:221], v10 offset:1824
	ds_read_b128 v[236:239], v10 offset:1840
	v_fmamk_f32 v30, v51, 0xbd800000, v31
	v_fmamk_f32 v33, v161, 0xbd800000, v30
	s_waitcnt lgkmcnt(4)
	v_pk_mul_f32 v[240:241], v[130:131], v[240:241]
	v_pk_mul_f32 v[194:195], v[130:131], v[194:195]
	v_pk_fma_f32 v[240:241], v[132:133], v[242:243], v[240:241]
	v_pk_fma_f32 v[194:195], v[132:133], v[196:197], v[194:195]
	v_pk_fma_f32 v[240:241], v[134:135], v[244:245], v[240:241]
	v_pk_fma_f32 v[194:195], v[134:135], v[198:199], v[194:195]
	v_pk_fma_f32 v[240:241], v[136:137], v[246:247], v[240:241]
	v_pk_fma_f32 v[194:195], v[136:137], v[200:201], v[194:195]
	v_pk_fma_f32 v[240:241], v[140:141], v[150:151], v[240:241]
	v_pk_fma_f32 v[194:195], v[140:141], v[202:203], v[194:195]
	v_pk_fma_f32 v[240:241], v[142:143], v[152:153], v[240:241]
	v_pk_fma_f32 v[194:195], v[142:143], v[204:205], v[194:195]
	v_pk_fma_f32 v[240:241], v[146:147], v[156:157], v[240:241]
	v_pk_fma_f32 v[194:195], v[146:147], v[206:207], v[194:195]
	v_pk_fma_f32 v[240:241], v[148:149], v[158:159], v[240:241]
	v_pk_fma_f32 v[194:195], v[148:149], v[208:209], v[194:195]
	v_add_f32_e32 v49, v240, v241
	v_add_f32_e32 v138, v194, v195
	v_add_f32_e32 v49, v122, v49
	v_add_f32_e32 v138, v122, v138
	v_max_f32_e64 v51, -v49, 0
	v_max_f32_e64 v161, -v138, 0
	v_mul_f32_e64 v129, |v49|, s13
	v_mul_f32_e64 v188, |v138|, s13
	v_exp_f32_e32 v129, v129
	v_exp_f32_e32 v188, v188
	v_add_f32_e32 v129, 1.0, v129
	v_add_f32_e32 v188, 1.0, v188
	v_log_f32_e32 v129, v129
	v_log_f32_e32 v188, v188
	v_fmac_f32_e32 v51, 0x3f317218, v129
	v_fmac_f32_e32 v161, 0x3f317218, v188
	ds_read_b128 v[240:243], v10 offset:1856
	ds_read_b128 v[244:247], v10 offset:1872
	ds_read_b128 v[150:153], v10 offset:1888
	ds_read_b128 v[156:159], v10 offset:1904
	ds_read_b128 v[194:197], v10 offset:1920
	ds_read_b128 v[198:201], v10 offset:1936
	ds_read_b128 v[202:205], v10 offset:1952
	ds_read_b128 v[206:209], v10 offset:1968
	v_fmamk_f32 v32, v51, 0xbd800000, v33
	v_fmamk_f32 v35, v161, 0xbd800000, v32
	s_waitcnt lgkmcnt(4)
	v_pk_mul_f32 v[210:211], v[130:131], v[210:211]
	v_pk_mul_f32 v[240:241], v[130:131], v[240:241]
	v_pk_fma_f32 v[210:211], v[132:133], v[212:213], v[210:211]
	v_pk_fma_f32 v[240:241], v[132:133], v[242:243], v[240:241]
	v_pk_fma_f32 v[210:211], v[134:135], v[214:215], v[210:211]
	v_pk_fma_f32 v[240:241], v[134:135], v[244:245], v[240:241]
	v_pk_fma_f32 v[210:211], v[136:137], v[216:217], v[210:211]
	v_pk_fma_f32 v[240:241], v[136:137], v[246:247], v[240:241]
	v_pk_fma_f32 v[210:211], v[140:141], v[218:219], v[210:211]
	v_pk_fma_f32 v[240:241], v[140:141], v[150:151], v[240:241]
	v_pk_fma_f32 v[210:211], v[142:143], v[220:221], v[210:211]
	v_pk_fma_f32 v[240:241], v[142:143], v[152:153], v[240:241]
	v_pk_fma_f32 v[210:211], v[146:147], v[236:237], v[210:211]
	v_pk_fma_f32 v[240:241], v[146:147], v[156:157], v[240:241]
	v_pk_fma_f32 v[210:211], v[148:149], v[238:239], v[210:211]
	v_pk_fma_f32 v[240:241], v[148:149], v[158:159], v[240:241]
	v_add_f32_e32 v49, v210, v211
	v_add_f32_e32 v138, v240, v241
	v_add_f32_e32 v49, v122, v49
	v_add_f32_e32 v138, v122, v138
	v_max_f32_e64 v51, -v49, 0
	v_max_f32_e64 v161, -v138, 0
	v_mul_f32_e64 v129, |v49|, s13
	v_mul_f32_e64 v188, |v138|, s13
	v_exp_f32_e32 v129, v129
	v_exp_f32_e32 v188, v188
	v_add_f32_e32 v129, 1.0, v129
	v_add_f32_e32 v188, 1.0, v188
	v_log_f32_e32 v129, v129
	v_log_f32_e32 v188, v188
	v_fmac_f32_e32 v51, 0x3f317218, v129
	v_fmac_f32_e32 v161, 0x3f317218, v188
	ds_read_b128 v[210:213], v10 offset:1984
	ds_read_b128 v[214:217], v10 offset:2000
	ds_read_b128 v[218:221], v10 offset:2016
	ds_read_b128 v[236:239], v10 offset:2032
	v_fmamk_f32 v34, v51, 0xbd800000, v35
	v_fmamk_f32 v42, v161, 0xbd800000, v34
	s_waitcnt lgkmcnt(0)
	v_pk_mul_f32 v[194:195], v[130:131], v[194:195]
	v_pk_mul_f32 v[210:211], v[130:131], v[210:211]
	v_pk_fma_f32 v[194:195], v[132:133], v[196:197], v[194:195]
	v_pk_fma_f32 v[210:211], v[132:133], v[212:213], v[210:211]
	v_pk_fma_f32 v[194:195], v[134:135], v[198:199], v[194:195]
	v_pk_fma_f32 v[210:211], v[134:135], v[214:215], v[210:211]
	v_pk_fma_f32 v[194:195], v[136:137], v[200:201], v[194:195]
	v_pk_fma_f32 v[210:211], v[136:137], v[216:217], v[210:211]
	v_pk_fma_f32 v[194:195], v[140:141], v[202:203], v[194:195]
	v_pk_fma_f32 v[210:211], v[140:141], v[218:219], v[210:211]
	v_pk_fma_f32 v[194:195], v[142:143], v[204:205], v[194:195]
	v_pk_fma_f32 v[210:211], v[142:143], v[220:221], v[210:211]
	v_pk_fma_f32 v[194:195], v[146:147], v[206:207], v[194:195]
	v_pk_fma_f32 v[210:211], v[146:147], v[236:237], v[210:211]
	v_pk_fma_f32 v[194:195], v[148:149], v[208:209], v[194:195]
	v_pk_fma_f32 v[210:211], v[148:149], v[238:239], v[210:211]
	v_add_f32_e32 v49, v194, v195
	v_add_f32_e32 v138, v210, v211
	v_add_f32_e32 v49, v122, v49
	v_add_f32_e32 v138, v122, v138
	v_max_f32_e64 v51, -v49, 0
	v_max_f32_e64 v161, -v138, 0
	v_mul_f32_e64 v129, |v49|, s13
	v_mul_f32_e64 v188, |v138|, s13
	v_exp_f32_e32 v129, v129
	v_exp_f32_e32 v188, v188
	v_add_f32_e32 v129, 1.0, v129
	v_add_f32_e32 v188, 1.0, v188
	v_log_f32_e32 v129, v129
	v_log_f32_e32 v188, v188
	v_fmac_f32_e32 v51, 0x3f317218, v129
	v_fmac_f32_e32 v161, 0x3f317218, v188
	v_fmamk_f32 v36, v51, 0xbd800000, v42
	v_fmamk_f32 v43, v161, 0xbd800000, v36
	v_lshl_add_u32 v10, v38, 2, s0
	ds_write_b32 v10, v43
	v_add_u32_e32 v10, s0, v40
	s_waitcnt lgkmcnt(0)
	s_barrier
	ds_read2st64_b32 v[46:47], v10 offset1:4
	s_movk_i32 s0, 0x100
	v_cmp_gt_u32_e32 vcc, s0, v38
	v_readlane_b32 s0, v254, 63
	v_readlane_b32 s1, v255, 0
	s_waitcnt lgkmcnt(0)
	v_cndmask_b32_e64 v40, v46, 0, vcc
	v_add_f32_e32 v44, v6, v40
	v_add_f32_e32 v10, v46, v47
	v_mul_f32_e32 v47, 0x3fb8aa3b, v44
	v_exp_f32_e32 v47, v47
	v_lshlrev_b32_e32 v6, 16, v128
	v_cndmask_b32_e64 v37, v10, 0, s[0:1]
	v_mul_f32_e32 v6, 0x3e000000, v6
	v_mul_f32_e32 v6, v6, v47
	v_sub_f32_e32 v44, v37, v44
	v_mul_f32_e32 v44, 0x3fb8aa3b, v44
	v_cvt_pk_bf16_f32 v47, v6, v6
	v_mul_i32_i24_e32 v6, 0x2100, v121
	v_exp_f32_e32 v44, v44
	v_or_b32_sdwa v6, v6, v38 dst_sel:DWORD dst_unused:UNUSED_PAD src0_sel:DWORD src1_sel:BYTE_0
	v_lshl_add_u32 v6, v6, 1, 0
	v_add_f32_e32 v8, v8, v40
	v_lshlrev_b32_e32 v46, 16, v127
	ds_write_b16_d16_hi v6, v47
	v_mul_f32_e32 v47, 0x3fb8aa3b, v8
	v_mul_f32_e32 v44, v44, v46
	v_exp_f32_e32 v47, v47
	v_cvt_pk_bf16_f32 v44, v44, v44
	v_lshlrev_b32_e32 v46, 16, v126
	v_mul_f32_e32 v46, 0x3e000000, v46
	v_sub_f32_e32 v8, v37, v8
	v_mul_f32_e32 v46, v46, v47
	v_mul_f32_e32 v8, 0x3fb8aa3b, v8
	v_exp_f32_e32 v8, v8
	v_cvt_pk_bf16_f32 v46, v46, v46
	v_add_f32_e32 v7, v7, v40
	ds_write_b16_d16_hi v6, v46 offset:528
	v_mul_f32_e32 v46, 0x3fb8aa3b, v7
	v_sub_f32_e32 v7, v37, v7
	ds_write_b16_d16_hi v6, v44 offset:33792
	v_lshlrev_b32_e32 v44, 16, v125
	v_mul_f32_e32 v7, 0x3fb8aa3b, v7
	v_mul_f32_e32 v8, v8, v44
	v_exp_f32_e32 v7, v7
	v_exp_f32_e32 v46, v46
	v_cvt_pk_bf16_f32 v8, v8, v8
	ds_write_b16_d16_hi v6, v8 offset:34320
	v_lshlrev_b32_e32 v8, 16, v123
	v_lshlrev_b32_e32 v44, 16, v124
	v_mul_f32_e32 v44, 0x3e000000, v44
	v_mul_f32_e32 v7, v7, v8
	v_mul_f32_e32 v44, v44, v46
	v_cvt_pk_bf16_f32 v7, v7, v7
	v_cvt_pk_bf16_f32 v44, v44, v44
	ds_write_b16_d16_hi v6, v7 offset:34848
	v_add_f32_e32 v7, v11, v40
	ds_write_b16_d16_hi v6, v44 offset:1056
	v_mul_f32_e32 v44, 0x3fb8aa3b, v7
	v_sub_f32_e32 v7, v37, v7
	v_mul_f32_e32 v7, 0x3fb8aa3b, v7
	v_exp_f32_e32 v7, v7
	v_exp_f32_e32 v44, v44
	v_lshlrev_b32_e32 v8, 16, v118
	v_lshlrev_b32_e32 v11, 16, v119
	v_mul_f32_e32 v11, 0x3e000000, v11
	v_mul_f32_e32 v7, v7, v8
	v_mul_f32_e32 v11, v11, v44
	v_cvt_pk_bf16_f32 v7, v7, v7
	v_cvt_pk_bf16_f32 v11, v11, v11
	ds_write_b16_d16_hi v6, v7 offset:35376
	v_add_f32_e32 v7, v9, v40
	ds_write_b16_d16_hi v6, v11 offset:1584
	v_mul_f32_e32 v11, 0x3fb8aa3b, v7
	v_sub_f32_e32 v7, v37, v7
	v_mul_f32_e32 v7, 0x3fb8aa3b, v7
	v_exp_f32_e32 v7, v7
	v_exp_f32_e32 v11, v11
	v_lshlrev_b32_e32 v8, 16, v110
	v_lshlrev_b32_e32 v9, 16, v111
	v_mul_f32_e32 v7, v7, v8
	v_mul_f32_e32 v9, 0x3e000000, v9
	v_mul_f32_e32 v9, v9, v11
	v_cvt_pk_bf16_f32 v7, v7, v7
	ds_write_b16_d16_hi v6, v7 offset:35904
	v_add_f32_e32 v7, v13, v40
	v_cvt_pk_bf16_f32 v9, v9, v9
	v_mul_f32_e32 v11, 0x3fb8aa3b, v7
	v_sub_f32_e32 v7, v37, v7
	v_mul_f32_e32 v7, 0x3fb8aa3b, v7
	v_exp_f32_e32 v7, v7
	v_exp_f32_e32 v11, v11
	v_lshlrev_b32_e32 v8, 16, v102
	ds_write_b16_d16_hi v6, v9 offset:2112
	v_lshlrev_b32_e32 v9, 16, v103
	v_mul_f32_e32 v7, v7, v8
	v_mul_f32_e32 v9, 0x3e000000, v9
	v_mul_f32_e32 v9, v9, v11
	v_cvt_pk_bf16_f32 v7, v7, v7
	ds_write_b16_d16_hi v6, v7 offset:36432
	v_add_f32_e32 v7, v12, v40
	v_cvt_pk_bf16_f32 v9, v9, v9
	v_mul_f32_e32 v11, 0x3fb8aa3b, v7
	v_sub_f32_e32 v7, v37, v7
	v_mul_f32_e32 v7, 0x3fb8aa3b, v7
	v_exp_f32_e32 v7, v7
	v_exp_f32_e32 v11, v11
	v_lshlrev_b32_e32 v8, 16, v97
	ds_write_b16_d16_hi v6, v9 offset:2640
	v_lshlrev_b32_e32 v9, 16, v98
	v_mul_f32_e32 v7, v7, v8
	v_mul_f32_e32 v9, 0x3e000000, v9
	v_mul_f32_e32 v9, v9, v11
	v_cvt_pk_bf16_f32 v7, v7, v7
	ds_write_b16_d16_hi v6, v7 offset:36960
	v_add_f32_e32 v7, v15, v40
	v_cvt_pk_bf16_f32 v9, v9, v9
	v_mul_f32_e32 v11, 0x3fb8aa3b, v7
	v_sub_f32_e32 v7, v37, v7
	v_mul_f32_e32 v7, 0x3fb8aa3b, v7
	v_exp_f32_e32 v7, v7
	v_exp_f32_e32 v11, v11
	v_lshlrev_b32_e32 v8, 16, v95
	ds_write_b16_d16_hi v6, v9 offset:3168
	v_lshlrev_b32_e32 v9, 16, v96
	v_mul_f32_e32 v7, v7, v8
	v_mul_f32_e32 v9, 0x3e000000, v9
	v_mul_f32_e32 v9, v9, v11
	v_cvt_pk_bf16_f32 v7, v7, v7
	ds_write_b16_d16_hi v6, v7 offset:37488
	v_add_f32_e32 v7, v14, v40
	v_cvt_pk_bf16_f32 v9, v9, v9
	v_mul_f32_e32 v11, 0x3fb8aa3b, v7
	v_sub_f32_e32 v7, v37, v7
	v_mul_f32_e32 v7, 0x3fb8aa3b, v7
	v_exp_f32_e32 v7, v7
	v_exp_f32_e32 v11, v11
	v_lshlrev_b32_e32 v8, 16, v93
	ds_write_b16_d16_hi v6, v9 offset:3696
	v_lshlrev_b32_e32 v9, 16, v94
	v_mul_f32_e32 v7, v7, v8
	v_mul_f32_e32 v9, 0x3e000000, v9
	v_mul_f32_e32 v9, v9, v11
	v_cvt_pk_bf16_f32 v7, v7, v7
	ds_write_b16_d16_hi v6, v7 offset:38016
	v_add_f32_e32 v7, v17, v40
	v_cvt_pk_bf16_f32 v9, v9, v9
	v_mul_f32_e32 v11, 0x3fb8aa3b, v7
	v_sub_f32_e32 v7, v37, v7
	v_mul_f32_e32 v7, 0x3fb8aa3b, v7
	v_exp_f32_e32 v7, v7
	v_exp_f32_e32 v11, v11
	v_lshlrev_b32_e32 v8, 16, v91
	ds_write_b16_d16_hi v6, v9 offset:4224
	v_lshlrev_b32_e32 v9, 16, v92
	v_mul_f32_e32 v7, v7, v8
	v_mul_f32_e32 v9, 0x3e000000, v9
	v_mul_f32_e32 v9, v9, v11
	v_cvt_pk_bf16_f32 v7, v7, v7
	ds_write_b16_d16_hi v6, v7 offset:38544
	v_add_f32_e32 v7, v16, v40
	v_cvt_pk_bf16_f32 v9, v9, v9
	v_mul_f32_e32 v11, 0x3fb8aa3b, v7
	v_sub_f32_e32 v7, v37, v7
	v_mul_f32_e32 v7, 0x3fb8aa3b, v7
	v_exp_f32_e32 v7, v7
	v_exp_f32_e32 v11, v11
	v_lshlrev_b32_e32 v8, 16, v89
	ds_write_b16_d16_hi v6, v9 offset:4752
	v_lshlrev_b32_e32 v9, 16, v90
	v_mul_f32_e32 v7, v7, v8
	v_mul_f32_e32 v9, 0x3e000000, v9
	v_mul_f32_e32 v9, v9, v11
	v_cvt_pk_bf16_f32 v7, v7, v7
	ds_write_b16_d16_hi v6, v7 offset:39072
	v_add_f32_e32 v7, v19, v40
	v_cvt_pk_bf16_f32 v9, v9, v9
	v_mul_f32_e32 v11, 0x3fb8aa3b, v7
	v_sub_f32_e32 v7, v37, v7
	v_mul_f32_e32 v7, 0x3fb8aa3b, v7
	v_exp_f32_e32 v7, v7
	v_exp_f32_e32 v11, v11
	v_lshlrev_b32_e32 v8, 16, v87
	ds_write_b16_d16_hi v6, v9 offset:5280
	v_lshlrev_b32_e32 v9, 16, v88
	v_mul_f32_e32 v7, v7, v8
	v_mul_f32_e32 v9, 0x3e000000, v9
	v_mul_f32_e32 v9, v9, v11
	v_cvt_pk_bf16_f32 v7, v7, v7
	ds_write_b16_d16_hi v6, v7 offset:39600
	v_add_f32_e32 v7, v18, v40
	v_cvt_pk_bf16_f32 v9, v9, v9
	v_mul_f32_e32 v11, 0x3fb8aa3b, v7
	v_sub_f32_e32 v7, v37, v7
	v_mul_f32_e32 v7, 0x3fb8aa3b, v7
	v_exp_f32_e32 v7, v7
	v_exp_f32_e32 v11, v11
	v_lshlrev_b32_e32 v8, 16, v85
	ds_write_b16_d16_hi v6, v9 offset:5808
	v_lshlrev_b32_e32 v9, 16, v86
	v_mul_f32_e32 v7, v7, v8
	v_mul_f32_e32 v9, 0x3e000000, v9
	v_mul_f32_e32 v9, v9, v11
	v_cvt_pk_bf16_f32 v7, v7, v7
	ds_write_b16_d16_hi v6, v7 offset:40128
	v_add_f32_e32 v7, v21, v40
	v_cvt_pk_bf16_f32 v9, v9, v9
	v_mul_f32_e32 v11, 0x3fb8aa3b, v7
	v_sub_f32_e32 v7, v37, v7
	v_mul_f32_e32 v7, 0x3fb8aa3b, v7
	v_exp_f32_e32 v7, v7
	v_exp_f32_e32 v11, v11
	v_lshlrev_b32_e32 v8, 16, v84
	ds_write_b16_d16_hi v6, v9 offset:6336
	v_lshlrev_b32_e32 v9, 16, v83
	v_mul_f32_e32 v7, v7, v8
	v_mul_f32_e32 v9, 0x3e000000, v9
	v_mul_f32_e32 v9, v9, v11
	v_cvt_pk_bf16_f32 v7, v7, v7
	ds_write_b16_d16_hi v6, v7 offset:40656
	v_add_f32_e32 v7, v20, v40
	v_cvt_pk_bf16_f32 v9, v9, v9
	v_mul_f32_e32 v11, 0x3fb8aa3b, v7
	v_sub_f32_e32 v7, v37, v7
	v_mul_f32_e32 v7, 0x3fb8aa3b, v7
	v_exp_f32_e32 v7, v7
	v_exp_f32_e32 v11, v11
	v_lshlrev_b32_e32 v8, 16, v82
	ds_write_b16_d16_hi v6, v9 offset:6864
	v_lshlrev_b32_e32 v9, 16, v81
	v_mul_f32_e32 v7, v7, v8
	v_mul_f32_e32 v9, 0x3e000000, v9
	v_mul_f32_e32 v9, v9, v11
	v_cvt_pk_bf16_f32 v7, v7, v7
	ds_write_b16_d16_hi v6, v7 offset:41184
	v_add_f32_e32 v7, v23, v40
	v_cvt_pk_bf16_f32 v9, v9, v9
	v_mul_f32_e32 v11, 0x3fb8aa3b, v7
	v_sub_f32_e32 v7, v37, v7
	v_mul_f32_e32 v7, 0x3fb8aa3b, v7
	v_exp_f32_e32 v7, v7
	v_exp_f32_e32 v11, v11
	v_lshlrev_b32_e32 v8, 16, v80
	ds_write_b16_d16_hi v6, v9 offset:7392
	v_lshlrev_b32_e32 v9, 16, v79
	v_mul_f32_e32 v7, v7, v8
	v_mul_f32_e32 v9, 0x3e000000, v9
	v_mul_f32_e32 v9, v9, v11
	v_cvt_pk_bf16_f32 v7, v7, v7
	ds_write_b16_d16_hi v6, v7 offset:41712
	v_add_f32_e32 v7, v22, v40
	v_cvt_pk_bf16_f32 v9, v9, v9
	v_mul_f32_e32 v11, 0x3fb8aa3b, v7
	v_sub_f32_e32 v7, v37, v7
	v_mul_f32_e32 v7, 0x3fb8aa3b, v7
	v_exp_f32_e32 v7, v7
	v_exp_f32_e32 v11, v11
	v_lshlrev_b32_e32 v8, 16, v78
	ds_write_b16_d16_hi v6, v9 offset:7920
	v_lshlrev_b32_e32 v9, 16, v77
	v_mul_f32_e32 v7, v7, v8
	v_mul_f32_e32 v9, 0x3e000000, v9
	v_mul_f32_e32 v9, v9, v11
	v_cvt_pk_bf16_f32 v7, v7, v7
	ds_write_b16_d16_hi v6, v7 offset:42240
	v_add_f32_e32 v7, v25, v40
	v_cvt_pk_bf16_f32 v9, v9, v9
	v_mul_f32_e32 v11, 0x3fb8aa3b, v7
	v_sub_f32_e32 v7, v37, v7
	v_mul_f32_e32 v7, 0x3fb8aa3b, v7
	v_exp_f32_e32 v7, v7
	v_exp_f32_e32 v11, v11
	v_lshlrev_b32_e32 v8, 16, v76
	ds_write_b16_d16_hi v6, v9 offset:8448
	v_lshlrev_b32_e32 v9, 16, v75
	v_mul_f32_e32 v7, v7, v8
	v_mul_f32_e32 v9, 0x3e000000, v9
	v_mul_f32_e32 v9, v9, v11
	v_cvt_pk_bf16_f32 v7, v7, v7
	ds_write_b16_d16_hi v6, v7 offset:42768
	v_add_f32_e32 v7, v24, v40
	v_cvt_pk_bf16_f32 v9, v9, v9
	v_mul_f32_e32 v11, 0x3fb8aa3b, v7
	v_sub_f32_e32 v7, v37, v7
	v_mul_f32_e32 v7, 0x3fb8aa3b, v7
	v_exp_f32_e32 v7, v7
	v_exp_f32_e32 v11, v11
	v_lshlrev_b32_e32 v8, 16, v74
	ds_write_b16_d16_hi v6, v9 offset:8976
	v_lshlrev_b32_e32 v9, 16, v73
	v_mul_f32_e32 v7, v7, v8
	v_mul_f32_e32 v9, 0x3e000000, v9
	v_mul_f32_e32 v9, v9, v11
	v_cvt_pk_bf16_f32 v7, v7, v7
	ds_write_b16_d16_hi v6, v7 offset:43296
	v_add_f32_e32 v7, v27, v40
	v_cvt_pk_bf16_f32 v9, v9, v9
	v_mul_f32_e32 v11, 0x3fb8aa3b, v7
	v_sub_f32_e32 v7, v37, v7
	v_mul_f32_e32 v7, 0x3fb8aa3b, v7
	v_exp_f32_e32 v7, v7
	v_exp_f32_e32 v11, v11
	v_lshlrev_b32_e32 v8, 16, v72
	ds_write_b16_d16_hi v6, v9 offset:9504
	v_lshlrev_b32_e32 v9, 16, v71
	v_mul_f32_e32 v7, v7, v8
	v_mul_f32_e32 v9, 0x3e000000, v9
	v_mul_f32_e32 v9, v9, v11
	v_cvt_pk_bf16_f32 v7, v7, v7
	ds_write_b16_d16_hi v6, v7 offset:43824
	v_add_f32_e32 v7, v26, v40
	v_cvt_pk_bf16_f32 v9, v9, v9
	v_mul_f32_e32 v11, 0x3fb8aa3b, v7
	v_sub_f32_e32 v7, v37, v7
	v_mul_f32_e32 v7, 0x3fb8aa3b, v7
	v_exp_f32_e32 v7, v7
	v_exp_f32_e32 v11, v11
	v_lshlrev_b32_e32 v8, 16, v70
	ds_write_b16_d16_hi v6, v9 offset:10032
	v_lshlrev_b32_e32 v9, 16, v69
	v_mul_f32_e32 v7, v7, v8
	v_mul_f32_e32 v9, 0x3e000000, v9
	v_mul_f32_e32 v9, v9, v11
	v_cvt_pk_bf16_f32 v7, v7, v7
	ds_write_b16_d16_hi v6, v7 offset:44352
	v_add_f32_e32 v7, v29, v40
	v_cvt_pk_bf16_f32 v9, v9, v9
	v_mul_f32_e32 v11, 0x3fb8aa3b, v7
	v_sub_f32_e32 v7, v37, v7
	v_mul_f32_e32 v7, 0x3fb8aa3b, v7
	v_exp_f32_e32 v7, v7
	v_exp_f32_e32 v11, v11
	v_lshlrev_b32_e32 v8, 16, v68
	ds_write_b16_d16_hi v6, v9 offset:10560
	v_lshlrev_b32_e32 v9, 16, v67
	v_mul_f32_e32 v7, v7, v8
	v_mul_f32_e32 v9, 0x3e000000, v9
	v_mul_f32_e32 v9, v9, v11
	v_cvt_pk_bf16_f32 v7, v7, v7
	ds_write_b16_d16_hi v6, v7 offset:44880
	v_add_f32_e32 v7, v28, v40
	v_cvt_pk_bf16_f32 v9, v9, v9
	v_mul_f32_e32 v11, 0x3fb8aa3b, v7
	v_sub_f32_e32 v7, v37, v7
	v_mul_f32_e32 v7, 0x3fb8aa3b, v7
	v_exp_f32_e32 v7, v7
	v_exp_f32_e32 v11, v11
	v_lshlrev_b32_e32 v8, 16, v66
	ds_write_b16_d16_hi v6, v9 offset:11088
	v_lshlrev_b32_e32 v9, 16, v65
	v_mul_f32_e32 v7, v7, v8
	v_mul_f32_e32 v9, 0x3e000000, v9
	v_mul_f32_e32 v9, v9, v11
	v_cvt_pk_bf16_f32 v7, v7, v7
	ds_write_b16_d16_hi v6, v7 offset:45408
	v_add_f32_e32 v7, v31, v40
	v_cvt_pk_bf16_f32 v9, v9, v9
	v_mul_f32_e32 v11, 0x3fb8aa3b, v7
	v_sub_f32_e32 v7, v37, v7
	v_mul_f32_e32 v7, 0x3fb8aa3b, v7
	v_exp_f32_e32 v7, v7
	v_exp_f32_e32 v11, v11
	v_lshlrev_b32_e32 v8, 16, v64
	ds_write_b16_d16_hi v6, v9 offset:11616
	v_lshlrev_b32_e32 v9, 16, v63
	v_mul_f32_e32 v7, v7, v8
	v_mul_f32_e32 v9, 0x3e000000, v9
	v_mul_f32_e32 v9, v9, v11
	v_cvt_pk_bf16_f32 v7, v7, v7
	ds_write_b16_d16_hi v6, v7 offset:45936
	v_add_f32_e32 v7, v30, v40
	v_cvt_pk_bf16_f32 v9, v9, v9
	v_mul_f32_e32 v11, 0x3fb8aa3b, v7
	v_sub_f32_e32 v7, v37, v7
	v_mul_f32_e32 v7, 0x3fb8aa3b, v7
	v_exp_f32_e32 v7, v7
	v_exp_f32_e32 v11, v11
	v_lshlrev_b32_e32 v8, 16, v62
	ds_write_b16_d16_hi v6, v9 offset:12144
	v_lshlrev_b32_e32 v9, 16, v61
	v_mul_f32_e32 v7, v7, v8
	v_mul_f32_e32 v9, 0x3e000000, v9
	v_mul_f32_e32 v9, v9, v11
	v_cvt_pk_bf16_f32 v7, v7, v7
	ds_write_b16_d16_hi v6, v7 offset:46464
	v_add_f32_e32 v7, v33, v40
	v_cvt_pk_bf16_f32 v9, v9, v9
	v_mul_f32_e32 v11, 0x3fb8aa3b, v7
	v_sub_f32_e32 v7, v37, v7
	v_mul_f32_e32 v7, 0x3fb8aa3b, v7
	v_exp_f32_e32 v7, v7
	v_exp_f32_e32 v11, v11
	v_lshlrev_b32_e32 v8, 16, v60
	ds_write_b16_d16_hi v6, v9 offset:12672
	v_lshlrev_b32_e32 v9, 16, v59
	v_mul_f32_e32 v7, v7, v8
	v_mul_f32_e32 v9, 0x3e000000, v9
	v_mul_f32_e32 v9, v9, v11
	v_cvt_pk_bf16_f32 v7, v7, v7
	ds_write_b16_d16_hi v6, v7 offset:46992
	v_add_f32_e32 v7, v32, v40
	v_cvt_pk_bf16_f32 v9, v9, v9
	v_mul_f32_e32 v11, 0x3fb8aa3b, v7
	v_sub_f32_e32 v7, v37, v7
	v_mul_f32_e32 v7, 0x3fb8aa3b, v7
	v_exp_f32_e32 v7, v7
	v_exp_f32_e32 v11, v11
	v_lshlrev_b32_e32 v8, 16, v58
	ds_write_b16_d16_hi v6, v9 offset:13200
	v_lshlrev_b32_e32 v9, 16, v57
	v_mul_f32_e32 v7, v7, v8
	v_mul_f32_e32 v9, 0x3e000000, v9
	v_mul_f32_e32 v9, v9, v11
	v_cvt_pk_bf16_f32 v7, v7, v7
	ds_write_b16_d16_hi v6, v7 offset:47520
	v_add_f32_e32 v7, v35, v40
	v_cvt_pk_bf16_f32 v9, v9, v9
	v_mul_f32_e32 v11, 0x3fb8aa3b, v7
	v_sub_f32_e32 v7, v37, v7
	v_mul_f32_e32 v7, 0x3fb8aa3b, v7
	v_exp_f32_e32 v7, v7
	v_exp_f32_e32 v11, v11
	v_lshlrev_b32_e32 v8, 16, v56
	ds_write_b16_d16_hi v6, v9 offset:13728
	v_lshlrev_b32_e32 v9, 16, v55
	v_mul_f32_e32 v7, v7, v8
	v_mul_f32_e32 v9, 0x3e000000, v9
	v_mul_f32_e32 v9, v9, v11
	v_cvt_pk_bf16_f32 v7, v7, v7
	ds_write_b16_d16_hi v6, v7 offset:48048
	v_add_f32_e32 v7, v34, v40
	v_cvt_pk_bf16_f32 v9, v9, v9
	v_mul_f32_e32 v11, 0x3fb8aa3b, v7
	v_sub_f32_e32 v7, v37, v7
	v_mul_f32_e32 v7, 0x3fb8aa3b, v7
	v_exp_f32_e32 v7, v7
	v_exp_f32_e32 v11, v11
	v_lshlrev_b32_e32 v8, 16, v54
	ds_write_b16_d16_hi v6, v9 offset:14256
	v_lshlrev_b32_e32 v9, 16, v53
	v_mul_f32_e32 v7, v7, v8
	v_mul_f32_e32 v9, 0x3e000000, v9
	v_mul_f32_e32 v9, v9, v11
	v_cvt_pk_bf16_f32 v7, v7, v7
	ds_write_b16_d16_hi v6, v7 offset:48576
	v_add_f32_e32 v7, v40, v42
	v_cvt_pk_bf16_f32 v9, v9, v9
	v_mul_f32_e32 v11, 0x3fb8aa3b, v7
	v_sub_f32_e32 v7, v37, v7
	v_mul_f32_e32 v7, 0x3fb8aa3b, v7
	v_exp_f32_e32 v7, v7
	v_exp_f32_e32 v11, v11
	v_lshlrev_b32_e32 v8, 16, v52
	ds_write_b16_d16_hi v6, v9 offset:14784
	v_lshlrev_b32_e32 v9, 16, v50
	v_mul_f32_e32 v7, v7, v8
	v_mul_f32_e32 v9, 0x3e000000, v9
	v_mul_f32_e32 v9, v9, v11
	v_cvt_pk_bf16_f32 v7, v7, v7
	ds_write_b16_d16_hi v6, v7 offset:49104
	v_add_f32_e32 v7, v40, v36
	v_cvt_pk_bf16_f32 v9, v9, v9
	v_mul_f32_e32 v11, 0x3fb8aa3b, v7
	v_sub_f32_e32 v7, v37, v7
	v_mul_f32_e32 v7, 0x3fb8aa3b, v7
	v_exp_f32_e32 v7, v7
	v_exp_f32_e32 v11, v11
	v_lshlrev_b32_e32 v8, 16, v45
	ds_write_b16_d16_hi v6, v9 offset:15312
	v_lshlrev_b32_e32 v9, 16, v48
	v_mul_f32_e32 v7, v7, v8
	v_mul_f32_e32 v9, 0x3e000000, v9
	v_mul_f32_e32 v9, v9, v11
	v_cvt_pk_bf16_f32 v7, v7, v7
	ds_write_b16_d16_hi v6, v7 offset:49632
	v_add_f32_e32 v7, v40, v43
	v_cvt_pk_bf16_f32 v9, v9, v9
	v_mul_f32_e32 v11, 0x3fb8aa3b, v7
	v_sub_f32_e32 v7, v37, v7
	v_mul_f32_e32 v7, 0x3fb8aa3b, v7
	v_exp_f32_e32 v11, v11
	v_exp_f32_e32 v7, v7
	ds_write_b16_d16_hi v6, v9 offset:15840
	v_lshlrev_b32_e32 v9, 16, v41
	v_lshlrev_b32_e32 v8, 16, v39
	v_mul_f32_e32 v9, 0x3e000000, v9
	v_mul_f32_e32 v9, v9, v11
	v_mul_f32_e32 v7, v7, v8
	v_readlane_b32 s0, v255, 1
	v_readlane_b32 s1, v255, 2
	v_cvt_pk_bf16_f32 v9, v9, v9
	v_cvt_pk_bf16_f32 v7, v7, v7
	s_and_b64 s[4:5], s[0:1], vcc
	ds_write_b16_d16_hi v6, v9 offset:16368
	ds_write_b16_d16_hi v6, v7 offset:50160
	s_and_saveexec_b64 s[0:1], s[4:5]
	s_cbranch_execz .LBB0_470
	v_mul_f32_e32 v6, 0x3fb8aa3b, v10
	s_lshl_b64 s[4:5], s[28:29], 10
	v_readlane_b32 s6, v250, 37
	v_exp_f32_e32 v8, v6
	v_readlane_b32 s7, v250, 38
	s_add_u32 s4, s6, s4
	s_addc_u32 s5, s7, s5
	v_mov_b32_e32 v39, v139
	v_lshl_add_u64 v[6:7], v[38:39], 2, s[4:5]
	global_store_dword v[6:7], v8, off
